# v40: v36 + all flat_load of global pointers issued as global_load (no lgkmcnt coupling; attention K/V prefetch no longer stalls the LDS waits)
# baseline (speedup 1.0000x reference)
.LBB0_21:
	s_add_i32 s6, s72, 0xffffed00
	s_lshr_b32 s9, s6, 4
	s_lshl_b32 s6, s9, 1
	s_bfe_u32 s7, s72, 0x10002
	s_or_b32 s14, s6, s7
	s_lshl_b64 s[6:7], s[14:15], 16
	s_add_u32 s6, s4, s6
	s_addc_u32 s7, s5, s7
	s_lshl_b32 s4, s9, 2
	s_or_b32 s14, s4, s8
	s_lshl_b32 s8, s72, 6
	s_and_b32 s8, s8, 0xc0
	s_lshl_b64 s[4:5], s[14:15], 15
	v_mov_b32_e32 v12, v0
	s_lshl_b32 s9, s8, 2
	s_add_u32 s6, s6, s9
	v_ashrrev_i32_e32 v10, 4, v12
	v_lshlrev_b32_e32 v2, 4, v12
	s_addc_u32 s7, s7, 0
	v_and_b32_e32 v62, 0xf0, v2
	v_ashrrev_i32_e32 v11, 31, v10
	v_lshl_add_u64 v[2:3], s[6:7], 0, v[62:63]
	v_lshlrev_b64 v[4:5], 10, v[10:11]
	v_lshl_add_u64 v[6:7], v[2:3], 0, v[4:5]
	global_load_dwordx4 v[2:5], v[6:7], off nt
	v_add_co_u32_e32 v6, vcc, s29, v6
	v_ashrrev_i32_e32 v11, 3, v12
	s_nop 0
	v_addc_co_u32_e32 v7, vcc, 0, v7, vcc
	global_load_dwordx4 v[6:9], v[6:7], off nt
	v_lshlrev_b32_e32 v12, 3, v12
	v_mul_lo_u32 v10, v10, s28
	v_and_b32_e32 v12, 56, v12
	v_add3_u32 v10, s3, v62, v10
	v_lshlrev_b32_e32 v13, 2, v11
	v_mul_u32_u24_e32 v14, 0x104, v12
	v_add_u32_e32 v15, 0x2080, v10
	v_add_u32_e32 v16, 0x2088, v10
	v_add3_u32 v13, s3, v14, v13
	v_lshlrev_b32_e32 v62, 1, v12
	s_waitcnt vmcnt(0) lgkmcnt(0)
	ds_write2_b32 v10, v2, v3 offset1:1
	ds_write2_b32 v10, v4, v5 offset0:2 offset1:3
	ds_write2_b32 v15, v6, v7 offset1:1
	ds_write2_b32 v16, v8, v9 offset1:1
	v_add_u32_e32 v6, s8, v11
	v_ashrrev_i32_e32 v7, 31, v6
	s_waitcnt lgkmcnt(0)
	s_barrier
	ds_read2_b32 v[2:3], v13 offset1:65
	v_lshl_add_u64 v[8:9], v[48:49], 0, s[4:5]
	v_lshlrev_b64 v[6:7], 7, v[6:7]
	s_waitcnt lgkmcnt(0)
	v_cvt_pk_bf16_f32 v2, v2, v3
	ds_read2_b32 v[4:5], v13 offset0:130 offset1:195
	v_add_u32_e32 v10, 0x400, v13
	v_lshl_add_u64 v[6:7], v[8:9], 0, v[6:7]
	s_waitcnt lgkmcnt(0)
	v_cvt_pk_bf16_f32 v3, v4, v5
	ds_read2_b32 v[4:5], v10 offset0:4 offset1:69
	v_lshl_add_u64 v[6:7], v[6:7], 0, v[62:63]
	s_mov_b64 s[4:5], 0
	s_waitcnt lgkmcnt(0)
	v_cvt_pk_bf16_f32 v4, v4, v5
	ds_read2_b32 v[10:11], v10 offset0:134 offset1:199
	s_waitcnt lgkmcnt(0)
	v_cvt_pk_bf16_f32 v5, v10, v11
	global_store_dwordx4 v[6:7], v[2:5], off
	s_barrier

.LBB0_45:
	s_andn2_b64 vcc, exec, s[4:5]
	s_cbranch_vccnz .LBB0_47
	ds_read_b64 v[2:3], v63 offset:208
	s_add_i32 s4, s72, 0xffffef00
	s_lshr_b32 s14, s4, 8
	s_lshl_b64 s[4:5], s[14:15], 22
	v_mov_b32_e32 v10, v0
	s_waitcnt lgkmcnt(0)
	v_readfirstlane_b32 s7, v2
	v_readfirstlane_b32 s6, v3
	s_add_u32 s7, s7, s4
	s_addc_u32 s8, s6, s5
	s_lshl_b32 s6, s72, 6
	s_and_b32 s9, s6, 0x3c0
	s_lshl_b32 s6, s72, 2
	s_lshl_b64 s[4:5], s[14:15], 21
	s_and_b32 s14, s6, 0x3c0
	s_lshl_b32 s6, s14, 2
	v_ashrrev_i32_e32 v11, 4, v10
	s_add_u32 s6, s7, s6
	v_lshlrev_b32_e32 v2, 4, v10
	v_add_u32_e32 v8, s9, v11
	s_addc_u32 s7, s8, 0
	v_and_b32_e32 v62, 0xf0, v2
	v_ashrrev_i32_e32 v9, 31, v8
	v_lshl_add_u64 v[6:7], s[6:7], 0, v[62:63]
	v_lshlrev_b64 v[2:3], 12, v[8:9]
	v_add_u32_e32 v8, 32, v8
	v_lshl_add_u64 v[2:3], v[6:7], 0, v[2:3]
	v_ashrrev_i32_e32 v9, 31, v8
	global_load_dwordx4 v[2:5], v[2:3], off nt
	v_lshlrev_b64 v[8:9], 12, v[8:9]
	v_lshl_add_u64 v[6:7], v[6:7], 0, v[8:9]
	global_load_dwordx4 v[6:9], v[6:7], off nt
	v_mul_lo_u32 v11, v11, s28
	v_ashrrev_i32_e32 v12, 3, v10
	v_lshlrev_b32_e32 v10, 3, v10
	v_add3_u32 v11, s3, v62, v11
	v_and_b32_e32 v13, 56, v10
	v_add_u32_e32 v15, 0x2080, v11
	v_add_u32_e32 v16, 0x2088, v11
	v_lshlrev_b32_e32 v10, 2, v12
	v_mul_u32_u24_e32 v14, 0x104, v13
	v_add3_u32 v10, s3, v14, v10
	v_lshlrev_b32_e32 v62, 1, v13
	s_waitcnt vmcnt(0) lgkmcnt(0)
	ds_write2_b32 v11, v2, v3 offset1:1
	ds_write2_b32 v11, v4, v5 offset0:2 offset1:3
	ds_write2_b32 v15, v6, v7 offset1:1
	ds_write2_b32 v16, v8, v9 offset1:1
	v_add_u32_e32 v8, s14, v12
	v_ashrrev_i32_e32 v9, 31, v8
	v_lshl_add_u64 v[6:7], v[52:53], 0, s[4:5]
	v_lshlrev_b64 v[8:9], 11, v[8:9]
	s_waitcnt lgkmcnt(0)
	s_barrier
	ds_read2_b32 v[2:3], v10 offset1:65
	s_lshl_b32 s14, s9, 1
	v_lshl_add_u64 v[6:7], v[6:7], 0, v[8:9]
	s_waitcnt lgkmcnt(0)
	v_cvt_pk_bf16_f32 v2, v2, v3
	ds_read2_b32 v[4:5], v10 offset0:130 offset1:195
	v_add_u32_e32 v10, 0x400, v10
	v_lshl_add_u64 v[6:7], v[6:7], 0, s[14:15]
	s_waitcnt lgkmcnt(0)
	v_cvt_pk_bf16_f32 v3, v4, v5
	ds_read2_b32 v[4:5], v10 offset0:4 offset1:69
	v_lshl_add_u64 v[6:7], v[6:7], 0, v[62:63]
	s_waitcnt lgkmcnt(0)
	v_cvt_pk_bf16_f32 v4, v4, v5
	ds_read2_b32 v[10:11], v10 offset0:134 offset1:199
	s_waitcnt lgkmcnt(0)
	v_cvt_pk_bf16_f32 v5, v10, v11
	global_store_dwordx4 v[6:7], v[2:5], off
	s_barrier

.LBB0_48:
	s_andn2_b64 vcc, exec, s[4:5]
	s_cbranch_vccnz .LBB0_50
	ds_read_b64 v[2:3], v63 offset:200
	s_add_i32 s4, s72, 0xfffff100
	s_lshr_b32 s14, s4, 6
	s_lshl_b64 s[4:5], s[14:15], 20
	v_mov_b32_e32 v10, v0
	s_waitcnt lgkmcnt(0)
	v_readfirstlane_b32 s7, v2
	v_readfirstlane_b32 s6, v3
	s_add_u32 s7, s7, s4
	s_addc_u32 s8, s6, s5
	s_lshl_b32 s6, s72, 6
	s_and_b32 s9, s6, 0xc0
	s_lshl_b32 s6, s72, 4
	s_lshl_b64 s[4:5], s[14:15], 19
	s_and_b32 s14, s6, 0x3c0
	s_lshl_b32 s6, s14, 2
	v_ashrrev_i32_e32 v11, 4, v10
	s_add_u32 s6, s7, s6
	v_lshlrev_b32_e32 v2, 4, v10
	v_add_u32_e32 v8, s9, v11
	s_addc_u32 s7, s8, 0
	v_and_b32_e32 v62, 0xf0, v2
	v_ashrrev_i32_e32 v9, 31, v8
	v_lshl_add_u64 v[6:7], s[6:7], 0, v[62:63]
	v_lshlrev_b64 v[2:3], 12, v[8:9]
	v_add_u32_e32 v8, 32, v8
	v_lshl_add_u64 v[2:3], v[6:7], 0, v[2:3]
	v_ashrrev_i32_e32 v9, 31, v8
	global_load_dwordx4 v[2:5], v[2:3], off nt
	v_lshlrev_b64 v[8:9], 12, v[8:9]
	v_lshl_add_u64 v[6:7], v[6:7], 0, v[8:9]
	global_load_dwordx4 v[6:9], v[6:7], off nt
	v_mul_lo_u32 v11, v11, s28
	v_ashrrev_i32_e32 v12, 3, v10
	v_lshlrev_b32_e32 v10, 3, v10
	v_add3_u32 v11, s3, v62, v11
	v_and_b32_e32 v13, 56, v10
	v_add_u32_e32 v15, 0x2080, v11
	v_add_u32_e32 v16, 0x2088, v11
	v_lshlrev_b32_e32 v10, 2, v12
	v_mul_u32_u24_e32 v14, 0x104, v13
	v_add3_u32 v10, s3, v14, v10
	v_lshlrev_b32_e32 v62, 1, v13
	s_waitcnt vmcnt(0) lgkmcnt(0)
	ds_write2_b32 v11, v2, v3 offset1:1
	ds_write2_b32 v11, v4, v5 offset0:2 offset1:3
	ds_write2_b32 v15, v6, v7 offset1:1
	ds_write2_b32 v16, v8, v9 offset1:1
	v_add_u32_e32 v8, s14, v12
	v_ashrrev_i32_e32 v9, 31, v8
	v_lshl_add_u64 v[6:7], v[54:55], 0, s[4:5]
	v_lshlrev_b64 v[8:9], 9, v[8:9]
	s_waitcnt lgkmcnt(0)
	s_barrier
	ds_read2_b32 v[2:3], v10 offset1:65
	s_lshl_b32 s14, s9, 1
	v_lshl_add_u64 v[6:7], v[6:7], 0, v[8:9]
	s_waitcnt lgkmcnt(0)
	v_cvt_pk_bf16_f32 v2, v2, v3
	ds_read2_b32 v[4:5], v10 offset0:130 offset1:195
	v_add_u32_e32 v10, 0x400, v10
	v_lshl_add_u64 v[6:7], v[6:7], 0, s[14:15]
	s_waitcnt lgkmcnt(0)
	v_cvt_pk_bf16_f32 v3, v4, v5
	ds_read2_b32 v[4:5], v10 offset0:4 offset1:69
	v_lshl_add_u64 v[6:7], v[6:7], 0, v[62:63]
	s_waitcnt lgkmcnt(0)
	v_cvt_pk_bf16_f32 v4, v4, v5
	ds_read2_b32 v[10:11], v10 offset0:134 offset1:199
	s_waitcnt lgkmcnt(0)
	v_cvt_pk_bf16_f32 v5, v10, v11
	global_store_dwordx4 v[6:7], v[2:5], off
	s_barrier

.LBB0_51:
	s_andn2_b64 vcc, exec, s[4:5]
	s_cbranch_vccnz .LBB0_53
	ds_read_b64 v[2:3], v63 offset:80
	s_add_i32 s4, s72, 0xffffff40
	s_add_i32 s5, s72, 0xfffff820
	s_cmpk_lt_u32 s4, 0x720
	s_cselect_b32 s5, s4, s5
	s_cmpk_gt_u32 s4, 0x71f
	s_waitcnt lgkmcnt(0)
	v_readfirstlane_b32 s6, v2
	s_cselect_b32 s7, 0x1c80000, 0
	v_readfirstlane_b32 s4, v3
	s_cselect_b32 s14, 0xe40000, 0
	s_add_u32 s6, s6, s7
	s_addc_u32 s7, s4, 0
	s_lshl_b32 s4, s5, 6
	s_and_b32 s8, s4, 0x3c0
	s_lshl_b32 s4, s5, 2
	v_lshl_add_u64 v[10:11], v[46:47], 0, s[14:15]
	s_and_b32 s14, s4, 0x7fffffc0
	v_mov_b32_e32 v12, v0
	s_lshl_b64 s[4:5], s[14:15], 2
	s_add_u32 s4, s6, s4
	v_lshlrev_b32_e32 v2, 4, v12
	v_ashrrev_i32_e32 v13, 4, v12
	s_addc_u32 s5, s7, s5
	v_and_b32_e32 v62, 0xf0, v2
	v_lshl_add_u64 v[6:7], s[4:5], 0, v[62:63]
	v_add_u32_e32 v8, s8, v13
	v_mad_i64_i32 v[2:3], s[4:5], v8, s49, v[6:7]
	global_load_dwordx4 v[2:5], v[2:3], off nt
	v_add_u32_e32 v8, 32, v8
	v_mad_i64_i32 v[6:7], s[4:5], v8, s49, v[6:7]
	global_load_dwordx4 v[6:9], v[6:7], off nt
	v_mul_lo_u32 v13, v13, s28
	v_ashrrev_i32_e32 v14, 3, v12
	v_lshlrev_b32_e32 v12, 3, v12
	v_add3_u32 v13, s3, v62, v13
	v_and_b32_e32 v12, 56, v12
	v_add_u32_e32 v17, 0x2080, v13
	v_add_u32_e32 v18, 0x2088, v13
	v_lshlrev_b32_e32 v15, 2, v14
	v_mul_u32_u24_e32 v16, 0x104, v12
	v_add3_u32 v15, s3, v16, v15
	v_lshlrev_b32_e32 v62, 1, v12
	s_waitcnt vmcnt(0) lgkmcnt(0)
	ds_write2_b32 v13, v2, v3 offset1:1
	ds_write2_b32 v13, v4, v5 offset0:2 offset1:3
	ds_write2_b32 v17, v6, v7 offset1:1
	ds_write2_b32 v18, v8, v9 offset1:1
	v_add_u32_e32 v6, s14, v14
	v_ashrrev_i32_e32 v7, 31, v6
	v_lshlrev_b64 v[6:7], 11, v[6:7]
	s_waitcnt lgkmcnt(0)
	s_barrier
	ds_read2_b32 v[2:3], v15 offset1:65
	s_lshl_b32 s14, s8, 1
	v_lshl_add_u64 v[6:7], v[10:11], 0, v[6:7]
	s_waitcnt lgkmcnt(0)
	v_cvt_pk_bf16_f32 v2, v2, v3
	ds_read2_b32 v[4:5], v15 offset0:130 offset1:195
	v_add_u32_e32 v8, 0x400, v15
	v_lshl_add_u64 v[6:7], v[6:7], 0, s[14:15]
	s_waitcnt lgkmcnt(0)
	v_cvt_pk_bf16_f32 v3, v4, v5
	ds_read2_b32 v[4:5], v8 offset0:4 offset1:69
	v_lshl_add_u64 v[6:7], v[6:7], 0, v[62:63]
	s_waitcnt lgkmcnt(0)
	v_cvt_pk_bf16_f32 v4, v4, v5
	ds_read2_b32 v[8:9], v8 offset0:134 offset1:199
	s_waitcnt lgkmcnt(0)
	v_cvt_pk_bf16_f32 v5, v8, v9
	global_store_dwordx4 v[6:7], v[2:5], off
	s_barrier

.LBB0_56:
	s_or_b64 exec, exec, s[8:9]
	global_load_dword v6, v[6:7], off
	v_add_u32_e32 v10, 0x200, v9
	v_cmp_lt_i32_e32 vcc, s53, v9
	s_or_b64 s[6:7], vcc, s[6:7]
	s_waitcnt vmcnt(0) lgkmcnt(0)
	v_mul_f32_e32 v7, 0xbfb8aa3b, v6
	v_exp_f32_e32 v7, v7
	s_nop 0
	v_add_f32_e32 v7, 1.0, v7
	v_div_scale_f32 v9, s[8:9], v7, v7, v6
	v_rcp_f32_e32 v11, v9
	v_div_scale_f32 v12, vcc, v6, v7, v6
	v_fma_f32 v13, -v9, v11, 1.0
	v_fmac_f32_e32 v11, v13, v11
	v_mul_f32_e32 v13, v12, v11
	v_fma_f32 v14, -v9, v13, v12
	v_fmac_f32_e32 v13, v14, v11
	v_fma_f32 v9, -v9, v13, v12
	v_div_fmas_f32 v9, v9, v11, v13
	v_div_fixup_f32 v6, v9, v7, v6
	ds_write_b32 v8, v6
	v_add_u32_e32 v8, 0x800, v8
	v_mov_b32_e32 v9, v10
	s_andn2_b64 exec, exec, s[6:7]
	s_cbranch_execz .LBB0_61

.LBB0_62:
	v_lshl_add_u64 v[70:71], v[64:65], 0, s[6:7]
	v_add_co_u32_e32 v122, vcc, s54, v70
	ds_read_b128 v[10:13], v82
	ds_read_b128 v[6:9], v82 offset:16
	ds_read_b128 v[2:5], v82 offset:4096
	ds_read_b128 v[14:17], v82 offset:4112
	ds_read_b128 v[30:33], v82 offset:8192
	ds_read_b128 v[26:29], v82 offset:8208
	ds_read_b128 v[22:25], v82 offset:12288
	ds_read_b128 v[18:21], v82 offset:12304
	ds_read_b128 v[38:41], v82 offset:16384
	ds_read_b128 v[34:37], v82 offset:16400
	ds_read_b128 v[42:45], v82 offset:32
	ds_read_b128 v[84:87], v82 offset:48
	ds_read_b128 v[88:91], v82 offset:4128
	ds_read_b128 v[92:95], v82 offset:4144
	ds_read_b128 v[96:99], v82 offset:8224
	ds_read_b128 v[100:103], v82 offset:8240
	ds_read_b128 v[104:107], v82 offset:12320
	ds_read_b128 v[108:111], v82 offset:12336
	ds_read_b128 v[112:115], v82 offset:16416
	ds_read_b128 v[116:119], v82 offset:16432
	v_addc_co_u32_e32 v123, vcc, 0, v71, vcc
	v_add_co_u32_e32 v124, vcc, s55, v70
	global_load_dword v120, v[70:71], off nt
	s_nop 0
	v_addc_co_u32_e32 v125, vcc, 0, v71, vcc
	v_add_co_u32_e32 v126, vcc, s56, v70
	s_waitcnt lgkmcnt(0)
	v_mov_b32_e32 v150, v10
	v_addc_co_u32_e32 v127, vcc, 0, v71, vcc
	v_add_co_u32_e32 v128, vcc, s57, v70
	v_mov_b32_e32 v151, v2
	s_nop 0
	v_addc_co_u32_e32 v129, vcc, 0, v71, vcc
	v_add_co_u32_e32 v130, vcc, s58, v70
	v_mov_b32_e32 v2, v11
	s_nop 0
	v_addc_co_u32_e32 v131, vcc, 0, v71, vcc
	v_add_co_u32_e32 v132, vcc, s59, v70
	v_mov_b32_e32 v10, v12
	s_nop 0
	v_addc_co_u32_e32 v133, vcc, 0, v71, vcc
	v_add_co_u32_e32 v134, vcc, s60, v70
	v_mov_b32_e32 v11, v4
	s_nop 0
	v_addc_co_u32_e32 v135, vcc, 0, v71, vcc
	v_add_co_u32_e32 v136, vcc, s61, v70
	v_mov_b32_e32 v4, v13
	s_nop 0
	v_addc_co_u32_e32 v137, vcc, 0, v71, vcc
	v_add_co_u32_e32 v138, vcc, s62, v70
	v_mov_b32_e32 v12, v30
	s_nop 0
	v_addc_co_u32_e32 v139, vcc, 0, v71, vcc
	v_add_co_u32_e32 v140, vcc, s63, v70
	v_mov_b32_e32 v13, v22
	s_nop 0
	v_addc_co_u32_e32 v141, vcc, 0, v71, vcc
	v_add_co_u32_e32 v142, vcc, s64, v70
	v_mov_b32_e32 v22, v31
	s_nop 0
	v_addc_co_u32_e32 v143, vcc, 0, v71, vcc
	v_add_co_u32_e32 v144, vcc, s65, v70
	v_mov_b32_e32 v30, v32
	s_nop 0
	v_addc_co_u32_e32 v145, vcc, 0, v71, vcc
	v_add_co_u32_e32 v146, vcc, s66, v70
	v_mov_b32_e32 v31, v24
	s_nop 0
	v_addc_co_u32_e32 v147, vcc, 0, v71, vcc
	v_add_co_u32_e32 v148, vcc, s67, v70
	v_mov_b32_e32 v24, v33
	s_nop 0
	v_addc_co_u32_e32 v149, vcc, 0, v71, vcc
	v_add_co_u32_e32 v70, vcc, s68, v70
	v_mov_b32_e32 v32, v6
	s_nop 0
	v_addc_co_u32_e32 v71, vcc, 0, v71, vcc
	global_load_dword v122, v[122:123], off nt
	s_nop 0
	global_load_dword v124, v[124:125], off nt
	s_nop 0
	global_load_dword v126, v[126:127], off nt
	s_nop 0
	global_load_dword v128, v[128:129], off nt
	s_nop 0
	global_load_dword v130, v[130:131], off nt
	s_nop 0
	global_load_dword v132, v[132:133], off nt
	s_nop 0
	global_load_dword v134, v[134:135], off nt
	s_nop 0
	global_load_dword v136, v[136:137], off nt
	s_nop 0
	global_load_dword v138, v[138:139], off nt
	s_nop 0
	global_load_dword v140, v[140:141], off nt
	s_nop 0
	global_load_dword v142, v[142:143], off nt
	s_nop 0
	global_load_dword v144, v[144:145], off nt
	s_nop 0
	global_load_dword v146, v[146:147], off nt
	s_nop 0
	global_load_dword v148, v[148:149], off nt
	s_nop 0
	global_load_dword v70, v[70:71], off nt
	v_mov_b32_e32 v33, v14
	v_mov_b32_e32 v14, v7
	v_mov_b32_e32 v6, v8
	v_mov_b32_e32 v7, v16
	v_mov_b32_e32 v16, v9
	v_mov_b32_e32 v8, v26
	v_mov_b32_e32 v9, v18
	v_mov_b32_e32 v18, v27
	v_mov_b32_e32 v26, v28
	v_mov_b32_e32 v27, v20
	v_mov_b32_e32 v20, v29
	s_waitcnt vmcnt(0)
	v_pk_fma_f32 v[66:67], v[120:121], v[150:151], v[66:67] op_sel_hi:[0,1,1]
	v_pk_fma_f32 v[12:13], v[120:121], v[12:13], v[68:69] op_sel_hi:[0,1,1]
	v_fmac_f32_e32 v83, v120, v38
	v_mov_b32_e32 v28, v42
	v_mov_b32_e32 v29, v88
	v_mov_b32_e32 v88, v43
	v_mov_b32_e32 v42, v44
	v_mov_b32_e32 v43, v90
	v_mov_b32_e32 v90, v45
	v_mov_b32_e32 v44, v96
	v_mov_b32_e32 v45, v104
	v_mov_b32_e32 v104, v97
	v_mov_b32_e32 v96, v98
	v_mov_b32_e32 v97, v106
	v_mov_b32_e32 v106, v99
	v_mov_b32_e32 v98, v84
	v_mov_b32_e32 v99, v92
	v_mov_b32_e32 v92, v85
	v_mov_b32_e32 v84, v86
	v_mov_b32_e32 v85, v94
	v_mov_b32_e32 v94, v87
	v_mov_b32_e32 v86, v100
	v_mov_b32_e32 v87, v108
	v_mov_b32_e32 v108, v101
	s_add_u32 s6, s6, 0x30000
	v_mov_b32_e32 v100, v102
	v_mov_b32_e32 v101, v110
	s_addc_u32 s7, s7, 0
	v_mov_b32_e32 v110, v103
	v_add_u32_e32 v82, 64, v82
	s_cmp_eq_u32 s6, 0xc0000
	s_waitcnt lgkmcnt(0)
	v_pk_fma_f32 v[2:3], v[122:123], v[2:3], v[66:67] op_sel_hi:[0,1,1]
	v_pk_fma_f32 v[12:13], v[122:123], v[22:23], v[12:13] op_sel_hi:[0,1,1]
	v_fmac_f32_e32 v83, v122, v39
	v_pk_fma_f32 v[2:3], v[124:125], v[10:11], v[2:3] op_sel_hi:[0,1,1]
	v_pk_fma_f32 v[10:11], v[124:125], v[30:31], v[12:13] op_sel_hi:[0,1,1]
	v_fmac_f32_e32 v83, v124, v40
	v_pk_fma_f32 v[2:3], v[126:127], v[4:5], v[2:3] op_sel_hi:[0,1,1]
	v_pk_fma_f32 v[4:5], v[126:127], v[24:25], v[10:11] op_sel_hi:[0,1,1]
	v_fmac_f32_e32 v83, v126, v41
	v_pk_fma_f32 v[2:3], v[128:129], v[32:33], v[2:3] op_sel_hi:[0,1,1]
	v_pk_fma_f32 v[4:5], v[128:129], v[8:9], v[4:5] op_sel_hi:[0,1,1]
	v_fmac_f32_e32 v83, v128, v34
	v_pk_fma_f32 v[2:3], v[130:131], v[14:15], v[2:3] op_sel_hi:[0,1,1]
	v_pk_fma_f32 v[4:5], v[130:131], v[18:19], v[4:5] op_sel_hi:[0,1,1]
	v_fmac_f32_e32 v83, v130, v35
	v_pk_fma_f32 v[2:3], v[132:133], v[6:7], v[2:3] op_sel_hi:[0,1,1]
	v_pk_fma_f32 v[4:5], v[132:133], v[26:27], v[4:5] op_sel_hi:[0,1,1]
	v_fmac_f32_e32 v83, v132, v36
	v_pk_fma_f32 v[2:3], v[134:135], v[16:17], v[2:3] op_sel_hi:[0,1,1]
	v_pk_fma_f32 v[4:5], v[134:135], v[20:21], v[4:5] op_sel_hi:[0,1,1]
	v_fmac_f32_e32 v83, v134, v37
	v_pk_fma_f32 v[2:3], v[136:137], v[28:29], v[2:3] op_sel_hi:[0,1,1]
	v_pk_fma_f32 v[4:5], v[136:137], v[44:45], v[4:5] op_sel_hi:[0,1,1]
	v_fmac_f32_e32 v83, v136, v112
	v_pk_fma_f32 v[2:3], v[138:139], v[88:89], v[2:3] op_sel_hi:[0,1,1]
	v_pk_fma_f32 v[4:5], v[138:139], v[104:105], v[4:5] op_sel_hi:[0,1,1]
	v_fmac_f32_e32 v83, v138, v113
	v_pk_fma_f32 v[2:3], v[140:141], v[42:43], v[2:3] op_sel_hi:[0,1,1]
	v_pk_fma_f32 v[4:5], v[140:141], v[96:97], v[4:5] op_sel_hi:[0,1,1]
	v_fmac_f32_e32 v83, v140, v114
	v_pk_fma_f32 v[2:3], v[142:143], v[90:91], v[2:3] op_sel_hi:[0,1,1]
	v_pk_fma_f32 v[4:5], v[142:143], v[106:107], v[4:5] op_sel_hi:[0,1,1]
	v_fmac_f32_e32 v83, v142, v115
	v_pk_fma_f32 v[2:3], v[144:145], v[98:99], v[2:3] op_sel_hi:[0,1,1]
	v_pk_fma_f32 v[4:5], v[144:145], v[86:87], v[4:5] op_sel_hi:[0,1,1]
	v_fmac_f32_e32 v83, v144, v116
	v_pk_fma_f32 v[2:3], v[146:147], v[92:93], v[2:3] op_sel_hi:[0,1,1]
	v_pk_fma_f32 v[4:5], v[146:147], v[108:109], v[4:5] op_sel_hi:[0,1,1]
	v_fmac_f32_e32 v83, v146, v117
	v_pk_fma_f32 v[2:3], v[148:149], v[84:85], v[2:3] op_sel_hi:[0,1,1]
	v_pk_fma_f32 v[4:5], v[148:149], v[100:101], v[4:5] op_sel_hi:[0,1,1]
	v_fmac_f32_e32 v83, v148, v118
	v_pk_fma_f32 v[66:67], v[70:71], v[94:95], v[2:3] op_sel_hi:[0,1,1]
	v_pk_fma_f32 v[68:69], v[70:71], v[110:111], v[4:5] op_sel_hi:[0,1,1]
	v_fmac_f32_e32 v83, v70, v119
	s_cbranch_scc0 .LBB0_62
	v_lshl_add_u32 v2, v81, 2, v78
	v_mad_u64_u32 v[4:5], s[6:7], v62, s69, v[2:3]
	v_add_u32_e32 v3, 0x5000, v4
	v_cmp_gt_i32_e32 vcc, s70, v80
	ds_write2_b32 v3, v66, v67 offset1:32
	ds_write2_b32 v3, v68, v69 offset0:64 offset1:96
	ds_write_b32 v4, v83 offset:20992
	s_waitcnt lgkmcnt(0)
	s_barrier
	s_and_saveexec_b64 s[6:7], vcc
	s_cbranch_execz .LBB0_65
	ds_read_b64 v[4:5], v63 offset:64
	s_mul_i32 s5, s8, 0xc00
	s_add_i32 s5, s4, s5
	v_or_b32_e32 v6, s5, v81
	v_ashrrev_i32_e32 v7, 31, v6
	s_waitcnt lgkmcnt(0)
	v_readfirstlane_b32 s9, v5
	v_readfirstlane_b32 s14, v4
	s_ashr_i32 s5, s4, 31
	v_mov_b32_e32 v5, s9
	v_mov_b32_e32 v4, s14
	v_lshl_add_u64 v[4:5], v[6:7], 2, v[4:5]
	global_load_dword v20, v[4:5], off
	v_lshl_add_u32 v4, v62, 7, v2
	v_mad_u64_u32 v[2:3], s[20:21], s8, 5, v[62:63]
	v_add_u32_e32 v3, 0x5000, v4
	v_add_u32_e32 v6, 0x5400, v4
	v_add_u32_e32 v8, 0x5a00, v4
	v_add_u32_e32 v10, 0x5e00, v4
	v_add_u32_e32 v12, 0x6400, v4
	v_add_u32_e32 v14, 0x6800, v4
	v_add_u32_e32 v16, 0x6e00, v4
	v_add_u32_e32 v18, 0x7200, v4
	ds_read2_b32 v[4:5], v3 offset1:160
	ds_read2_b32 v[6:7], v6 offset0:64 offset1:224
	ds_read2_b32 v[8:9], v8 offset1:160
	ds_read2_b32 v[10:11], v10 offset0:64 offset1:224
	ds_read2_b32 v[12:13], v12 offset1:160
	ds_read2_b32 v[14:15], v14 offset0:64 offset1:224
	ds_read2_b32 v[16:17], v16 offset1:160
	ds_read2_b32 v[18:19], v18 offset0:64 offset1:224
	v_mul_lo_u32 v2, v2, s71
	v_ashrrev_i32_e32 v3, 31, v2
	v_lshl_add_u64 v[2:3], v[2:3], 2, v[56:57]
	v_lshlrev_b32_e32 v62, 2, v81
	v_lshl_add_u64 v[2:3], s[4:5], 2, v[2:3]
	v_lshl_add_u64 v[2:3], v[2:3], 0, v[62:63]
	s_waitcnt vmcnt(0) lgkmcnt(0)
	v_add_f32_e32 v4, v20, v4
	v_add_f32_e32 v4, v4, v5
	v_add_f32_e32 v4, v4, v6
	v_add_f32_e32 v4, v4, v7
	v_add_f32_e32 v4, v4, v8
	v_add_f32_e32 v4, v4, v9
	v_add_f32_e32 v4, v4, v10
	v_add_f32_e32 v4, v4, v11
	v_add_f32_e32 v4, v4, v12
	v_add_f32_e32 v4, v4, v13
	v_add_f32_e32 v4, v4, v14
	v_add_f32_e32 v4, v4, v15
	v_add_f32_e32 v4, v4, v16
	v_add_f32_e32 v4, v4, v17
	v_add_f32_e32 v4, v4, v18
	v_add_f32_e32 v4, v4, v19
	global_store_dword v[2:3], v4, off sc1

.LBB0_84:
	s_or_b64 exec, exec, s[4:5]
	v_lshlrev_b64 v[22:23], 12, v[22:23]
	v_lshl_add_u64 v[22:23], v[24:25], 0, v[22:23]
	v_lshl_add_u64 v[42:43], v[22:23], 0, v[12:13]
	global_load_dwordx4 v[22:25], v[42:43], off
	global_load_dwordx4 v[30:33], v[42:43], off offset:1024
	global_load_dwordx4 v[34:37], v[42:43], off offset:2048
	global_load_dwordx4 v[38:41], v[42:43], off offset:3072
	v_lshrrev_b32_e32 v2, 10, v2
	v_add_u32_e32 v2, 1, v2
	v_cndmask_b32_e64 v2, v2, 0, vcc
	v_mad_u64_u32 v[50:51], s[4:5], v2, s18, v[8:9]
	v_lshl_add_u64 v[54:55], v[50:51], 0, s[12:13]
	v_lshl_add_u64 v[52:53], v[54:55], 0, v[12:13]
	global_load_dwordx4 v[42:45], v[52:53], off
	global_load_dwordx4 v[46:49], v[6:7], off
	v_lshl_add_u64 v[56:57], v[50:51], 0, v[12:13]
	global_load_dwordx4 v[50:53], v[56:57], off
	v_lshlrev_b64 v[20:21], 11, v[20:21]
	v_lshl_add_u64 v[4:5], v[4:5], 0, s[52:53]
	s_waitcnt vmcnt(0) lgkmcnt(0)
	v_mov_b32_e32 v60, v23
	v_mov_b32_e32 v61, v31
	v_mov_b32_e32 v58, v22
	v_mov_b32_e32 v59, v30
	v_mov_b32_e32 v68, v35
	v_mov_b32_e32 v69, v39
	v_pk_mul_f32 v[60:61], v[60:61], v[60:61]
	v_mov_b32_e32 v62, v24
	v_mov_b32_e32 v63, v32
	v_mov_b32_e32 v66, v34
	v_mov_b32_e32 v67, v38
	v_pk_mul_f32 v[68:69], v[68:69], v[68:69]
	v_pk_fma_f32 v[58:59], v[58:59], v[58:59], v[60:61]
	v_mov_b32_e32 v64, v25
	v_mov_b32_e32 v65, v33
	v_mov_b32_e32 v70, v36
	v_mov_b32_e32 v71, v40
	v_pk_fma_f32 v[60:61], v[66:67], v[66:67], v[68:69]
	v_pk_fma_f32 v[58:59], v[62:63], v[62:63], v[58:59]
	v_mov_b32_e32 v72, v37
	v_mov_b32_e32 v73, v41
	v_pk_fma_f32 v[60:61], v[70:71], v[70:71], v[60:61]
	v_pk_fma_f32 v[58:59], v[64:65], v[64:65], v[58:59]
	v_pk_fma_f32 v[60:61], v[72:73], v[72:73], v[60:61]
	v_add_f32_e32 v2, v58, v59
	v_add_f32_e32 v2, v2, v60
	v_add_f32_e32 v2, v2, v61
	v_pk_add_f32 v[42:43], v[42:43], 1.0 op_sel_hi:[1,0]
	v_lshl_add_u64 v[58:59], v[10:11], 0, v[20:21]
	v_add_f32_dpp v2, v2, v2 row_ror:8 row_mask:0xf bank_mask:0xf bound_ctrl:1
	v_pk_add_f32 v[20:21], v[44:45], 1.0 op_sel_hi:[1,0]
	s_nop 0
	v_add_f32_dpp v2, v2, v2 row_ror:4 row_mask:0xf bank_mask:0xf bound_ctrl:1
	s_nop 1
	v_add_f32_dpp v2, v2, v2 row_ror:2 row_mask:0xf bank_mask:0xf bound_ctrl:1
	s_nop 1
	v_add_f32_dpp v2, v2, v2 row_ror:1 row_mask:0xf bank_mask:0xf bound_ctrl:1
	ds_bpermute_b32 v29, v26, v2
	s_waitcnt lgkmcnt(0)
	v_add_f32_e32 v2, v2, v29
	ds_bpermute_b32 v29, v27, v2
	s_waitcnt lgkmcnt(0)
	v_add_f32_e32 v2, v2, v29
	v_fmamk_f32 v2, v2, 0x3a800000, v28
	v_mul_f32_e32 v29, 0x4b800000, v2
	v_cmp_gt_f32_e32 vcc, s17, v2
	s_nop 1
	v_cndmask_b32_e32 v2, v2, v29, vcc
	v_rsq_f32_e32 v2, v2
	s_nop 0
	v_mul_f32_e32 v29, 0x45800000, v2
	v_cndmask_b32_e32 v2, v2, v29, vcc
	v_pk_mul_f32 v[22:23], v[22:23], v[2:3] op_sel_hi:[1,0]
	v_pk_mul_f32 v[24:25], v[24:25], v[2:3] op_sel_hi:[1,0]
	v_pk_mul_f32 v[22:23], v[46:47], v[22:23]
	v_pk_mul_f32 v[24:25], v[48:49], v[24:25]
	v_pk_fma_f32 v[22:23], v[42:43], v[22:23], v[50:51]
	v_pk_fma_f32 v[20:21], v[20:21], v[24:25], v[52:53]
	v_cvt_pk_bf16_f32 v22, v22, v23
	v_lshl_add_u64 v[24:25], v[54:55], 0, v[14:15]
	v_cvt_pk_bf16_f32 v23, v20, v21
	global_store_dwordx2 v[58:59], v[22:23], off
	global_load_dwordx4 v[20:23], v[6:7], off offset:1024
	s_nop 0
	global_load_dwordx4 v[42:45], v[24:25], off
	global_load_dwordx4 v[46:49], v[56:57], off offset:1024
	v_pk_mul_f32 v[30:31], v[30:31], v[2:3] op_sel_hi:[1,0]
	v_pk_mul_f32 v[24:25], v[32:33], v[2:3] op_sel_hi:[1,0]
	v_pk_mul_f32 v[34:35], v[34:35], v[2:3] op_sel_hi:[1,0]
	v_pk_mul_f32 v[38:39], v[38:39], v[2:3] op_sel_hi:[1,0]
	v_cmp_lt_i32_e32 vcc, s19, v4
	s_or_b64 s[8:9], vcc, s[8:9]
	s_waitcnt vmcnt(0) lgkmcnt(0)
	v_pk_mul_f32 v[20:21], v[20:21], v[30:31]
	v_pk_add_f32 v[30:31], v[42:43], 1.0 op_sel_hi:[1,0]
	v_pk_mul_f32 v[22:23], v[22:23], v[24:25]
	v_pk_add_f32 v[24:25], v[44:45], 1.0 op_sel_hi:[1,0]
	v_pk_fma_f32 v[20:21], v[30:31], v[20:21], v[46:47]
	v_pk_fma_f32 v[22:23], v[24:25], v[22:23], v[48:49]
	v_cvt_pk_bf16_f32 v20, v20, v21
	v_lshl_add_u64 v[24:25], v[54:55], 0, v[16:17]
	v_cvt_pk_bf16_f32 v21, v22, v23
	global_store_dwordx2 v[58:59], v[20:21], off offset:512
	global_load_dwordx4 v[20:23], v[6:7], off offset:2048
	s_nop 0
	global_load_dwordx4 v[30:33], v[24:25], off
	global_load_dwordx4 v[42:45], v[56:57], off offset:2048
	v_pk_mul_f32 v[24:25], v[36:37], v[2:3] op_sel_hi:[1,0]
	s_waitcnt vmcnt(0)
	v_pk_add_f32 v[30:31], v[30:31], 1.0 op_sel_hi:[1,0]
	s_waitcnt lgkmcnt(0)
	v_pk_mul_f32 v[20:21], v[20:21], v[34:35]
	v_pk_mul_f32 v[22:23], v[22:23], v[24:25]
	v_pk_add_f32 v[24:25], v[32:33], 1.0 op_sel_hi:[1,0]
	v_pk_fma_f32 v[20:21], v[30:31], v[20:21], v[42:43]
	v_pk_fma_f32 v[22:23], v[24:25], v[22:23], v[44:45]
	v_cvt_pk_bf16_f32 v20, v20, v21
	v_lshl_add_u64 v[24:25], v[54:55], 0, v[18:19]
	v_cvt_pk_bf16_f32 v21, v22, v23
	global_store_dwordx2 v[58:59], v[20:21], off offset:1024
	global_load_dwordx4 v[20:23], v[6:7], off offset:3072
	s_nop 0
	global_load_dwordx4 v[30:33], v[24:25], off
	global_load_dwordx4 v[34:37], v[56:57], off offset:3072
	v_pk_mul_f32 v[24:25], v[40:41], v[2:3] op_sel_hi:[1,0]
	s_waitcnt vmcnt(0)
	v_pk_add_f32 v[30:31], v[30:31], 1.0 op_sel_hi:[1,0]
	s_waitcnt lgkmcnt(0)
	v_pk_mul_f32 v[20:21], v[38:39], v[20:21]
	v_pk_mul_f32 v[22:23], v[24:25], v[22:23]
	v_pk_add_f32 v[24:25], v[32:33], 1.0 op_sel_hi:[1,0]
	v_pk_fma_f32 v[20:21], v[20:21], v[30:31], v[34:35]
	v_pk_fma_f32 v[22:23], v[22:23], v[24:25], v[36:37]
	v_cvt_pk_bf16_f32 v20, v20, v21
	s_nop 0
	v_cvt_pk_bf16_f32 v21, v22, v23
	global_store_dwordx2 v[58:59], v[20:21], off offset:1536
	s_andn2_b64 exec, exec, s[8:9]
	s_cbranch_execz .LBB0_89

.LBB0_513:
	s_or_b64 exec, exec, s[10:11]
	s_waitcnt lgkmcnt(0)
	s_barrier
	ds_read_b128 v[192:195], v101
	ds_read_b128 v[196:199], v101 offset:64
	ds_read_b128 v[244:247], v101 offset:4608
	ds_read_b128 v[248:251], v101 offset:4672
	global_load_dwordx4 v[94:97], v[102:103], off
	global_load_dwordx4 v[82:85], v[104:105], off
	global_load_dwordx4 v[90:93], v[106:107], off
	global_load_dwordx4 v[62:65], v[112:113], off
	global_load_dwordx4 v[18:21], v[126:127], off
	global_load_dwordx4 v[70:73], v[110:111], off
	global_load_dwordx4 v[42:45], v[118:119], off
	global_load_dwordx4 v[34:37], v[120:121], off
	global_load_dwordx4 v[2:5], v[128:129], off
	global_load_dwordx4 v[50:53], v[108:109], off
	global_load_dwordx4 v[38:41], v[122:123], off
	global_load_dwordx4 v[66:69], v[114:115], off
	global_load_dwordx4 v[30:33], v[124:125], off
	global_load_dwordx4 v[58:61], v[116:117], off
	global_load_dwordx4 v[14:17], v[136:137], off
	global_load_dwordx4 v[6:9], v[138:139], off
	global_load_dwordx4 v[22:25], v[102:103], off offset:64
	global_load_dwordx4 v[26:29], v[140:141], off
	global_load_dwordx4 v[46:49], v[142:143], off
	global_load_dwordx4 v[54:57], v[146:147], off
	global_load_dwordx4 v[74:77], v[126:127], off offset:64
	global_load_dwordx4 v[78:81], v[110:111], off offset:64
	global_load_dwordx4 v[86:89], v[118:119], off offset:64
	global_load_dwordx4 v[186:189], v[152:153], off
	v_or_b32_e32 v243, v10, v1
	v_cmp_gt_i32_e32 vcc, s37, v243
	v_cndmask_b32_e32 v11, v213, v214, vcc
	s_waitcnt lgkmcnt(0)
	s_waitcnt vmcnt(23)
	v_mfma_f32_16x16x32_bf16 v[94:97], v[94:97], v[192:195], 0
	s_waitcnt vmcnt(22)
	v_mfma_f32_16x16x32_bf16 v[82:85], v[82:85], v[192:195], 0
	s_waitcnt vmcnt(21)
	v_mfma_f32_16x16x32_bf16 v[90:93], v[90:93], v[244:247], 0
	s_waitcnt vmcnt(20)
	v_mfma_f32_16x16x32_bf16 v[62:65], v[62:65], v[192:195], 0
	s_waitcnt vmcnt(19)
	v_mfma_f32_16x16x32_bf16 v[18:21], v[18:21], v[192:195], 0
	s_waitcnt vmcnt(18)
	v_mfma_f32_16x16x32_bf16 v[70:73], v[70:73], v[192:195], 0
	s_waitcnt vmcnt(17)
	v_mfma_f32_16x16x32_bf16 v[42:45], v[42:45], v[192:195], 0
	s_waitcnt vmcnt(16)
	v_mfma_f32_16x16x32_bf16 v[34:37], v[34:37], v[192:195], 0
	s_waitcnt vmcnt(15)
	v_mfma_f32_16x16x32_bf16 v[2:5], v[2:5], v[192:195], 0
	s_waitcnt vmcnt(14)
	v_mfma_f32_16x16x32_bf16 v[50:53], v[50:53], v[244:247], 0
	s_waitcnt vmcnt(13)
	v_mfma_f32_16x16x32_bf16 v[38:41], v[38:41], v[244:247], 0
	s_waitcnt vmcnt(12)
	v_mfma_f32_16x16x32_bf16 v[66:69], v[66:69], v[244:247], 0
	s_waitcnt vmcnt(11)
	v_mfma_f32_16x16x32_bf16 v[30:33], v[30:33], v[244:247], 0
	s_waitcnt vmcnt(10)
	v_mfma_f32_16x16x32_bf16 v[58:61], v[58:61], v[244:247], 0
	s_waitcnt vmcnt(9)
	v_mfma_f32_16x16x32_bf16 v[14:17], v[14:17], v[244:247], 0
	s_waitcnt vmcnt(8)
	v_mfma_f32_16x16x32_bf16 v[6:9], v[6:9], v[244:247], 0
	s_waitcnt vmcnt(7)
	v_mfma_f32_16x16x32_bf16 v[94:97], v[22:25], v[196:199], v[94:97]
	global_load_dwordx4 v[22:25], v[158:159], off
	s_waitcnt vmcnt(7)
	v_mfma_f32_16x16x32_bf16 v[82:85], v[26:29], v[196:199], v[82:85]
	global_load_dwordx4 v[26:29], v[144:145], off
	s_waitcnt vmcnt(7)
	v_mfma_f32_16x16x32_bf16 v[90:93], v[46:49], v[248:251], v[90:93]
	global_load_dwordx4 v[46:49], v[154:155], off
	s_waitcnt vmcnt(7)
	v_mfma_f32_16x16x32_bf16 v[62:65], v[54:57], v[196:199], v[62:65]
	global_load_dwordx4 v[54:57], v[148:149], off
	s_waitcnt vmcnt(7)
	v_mfma_f32_16x16x32_bf16 v[18:21], v[74:77], v[196:199], v[18:21]
	global_load_dwordx4 v[74:77], v[156:157], off
	s_waitcnt vmcnt(7)
	v_mfma_f32_16x16x32_bf16 v[70:73], v[78:81], v[196:199], v[70:73]
	global_load_dwordx4 v[78:81], v[150:151], off
	s_waitcnt vmcnt(7)
	v_mfma_f32_16x16x32_bf16 v[42:45], v[86:89], v[196:199], v[42:45]
	global_load_dwordx4 v[86:89], v[160:161], off
	s_waitcnt vmcnt(7)
	v_mfma_f32_16x16x32_bf16 v[34:37], v[186:189], v[196:199], v[34:37]
	global_load_dwordx4 v[186:189], v[162:163], off
	s_waitcnt vmcnt(7)
	v_mfma_f32_16x16x32_bf16 v[2:5], v[22:25], v[196:199], v[2:5]
	s_waitcnt vmcnt(6)
	v_mfma_f32_16x16x32_bf16 v[50:53], v[26:29], v[248:251], v[50:53]
	s_waitcnt vmcnt(5)
	v_mfma_f32_16x16x32_bf16 v[38:41], v[46:49], v[248:251], v[38:41]
	s_waitcnt vmcnt(4)
	v_mfma_f32_16x16x32_bf16 v[66:69], v[54:57], v[248:251], v[66:69]
	s_waitcnt vmcnt(3)
	v_mfma_f32_16x16x32_bf16 v[30:33], v[74:77], v[248:251], v[30:33]
	s_waitcnt vmcnt(2)
	v_mfma_f32_16x16x32_bf16 v[58:61], v[78:81], v[248:251], v[58:61]
	s_waitcnt vmcnt(1)
	v_mfma_f32_16x16x32_bf16 v[14:17], v[86:89], v[248:251], v[14:17]
	s_waitcnt vmcnt(0)
	v_mfma_f32_16x16x32_bf16 v[6:9], v[186:189], v[248:251], v[6:9]
	v_cndmask_b32_e32 v12, v215, v216, vcc
	v_bitop3_b32 v130, v12, v10, v1 bitop3:0xe0
	v_mov_b64_e32 v[12:13], s[28:29]
	v_cndmask_b32_e64 v22, 10, 8, vcc
	v_and_b32_e32 v10, v11, v10
	v_mad_i64_i32 v[12:13], s[10:11], v243, s36, v[12:13]
	v_lshlrev_b64 v[22:23], v22, v[98:99]
	v_ashrrev_i32_e32 v11, 31, v10
	v_lshl_add_u64 v[22:23], v[22:23], 0, v[130:131]
	v_lshl_add_u64 v[190:191], v[12:13], 0, s[92:93]
	v_lshl_add_u64 v[204:205], v[10:11], 2, v[22:23]
	v_lshl_add_u64 v[10:11], v[190:191], 0, v[164:165]
	v_lshl_add_u64 v[188:189], v[12:13], 0, v[164:165]
	global_load_dwordx4 v[86:89], v[10:11], off
	global_load_dwordx4 v[46:49], v[188:189], off offset:3072
	global_load_dwordx4 v[192:195], v[166:167], off
	global_load_dwordx4 v[196:199], v[166:167], off offset:64
	global_load_dwordx4 v[54:57], v[188:189], off offset:3136
	global_load_dwordx4 v[26:29], v[188:189], off offset:3200
	global_load_dwordx4 v[244:247], v[166:167], off offset:128
	global_load_dwordx4 v[10:13], v[188:189], off offset:3264
	global_load_dwordx4 v[248:251], v[166:167], off offset:192
	global_load_dwordx4 v[74:77], v[188:189], off offset:2048
	global_load_dwordx4 v[78:81], v[174:175], off
	global_load_dwordx4 v[22:25], v[176:177], off
	v_mad_u64_u32 v[186:187], s[10:11], v204, s66, v[182:183]
	v_mad_i32_i24 v187, v205, s66, v187
	s_mov_b32 s10, 0x800000
	s_waitcnt vmcnt(0)
	global_store_dwordx4 v[186:187], v[86:89], off offset:512 sc1
	s_waitcnt lgkmcnt(0)
	s_nop 0
	v_pk_mul_f32 v[86:87], v[48:49], v[194:195]
	v_pk_mul_f32 v[224:225], v[46:47], v[192:193]
	v_pk_mul_f32 v[88:89], v[86:87], v[86:87]
	v_pk_mul_f32 v[192:193], v[224:225], v[224:225]
	v_pk_mul_f32 v[200:201], v[56:57], v[198:199]
	v_pk_mov_b32 v[194:195], v[192:193], v[88:89] op_sel:[1,0]
	v_mov_b32_e32 v193, v89
	v_pk_mul_f32 v[202:203], v[54:55], v[196:197]
	v_pk_add_f32 v[88:89], v[194:195], v[192:193]
	v_pk_mul_f32 v[192:193], v[200:201], v[200:201]
	v_pk_mul_f32 v[194:195], v[202:203], v[202:203]
	v_pk_mul_f32 v[198:199], v[26:27], v[244:245]
	v_pk_mov_b32 v[196:197], v[194:195], v[192:193] op_sel:[1,0]
	v_mov_b32_e32 v195, v193
	v_pk_add_f32 v[218:219], v[196:197], v[194:195]
	v_pk_mul_f32 v[194:195], v[10:11], v[248:249]
	v_pk_add_f32 v[88:89], v[88:89], v[88:89] op_sel:[0,1] op_sel_hi:[1,0]
	v_pk_add_f32 v[218:219], v[218:219], v[218:219] op_sel:[0,1] op_sel_hi:[1,0]
	v_pk_mul_f32 v[196:197], v[28:29], v[246:247]
	v_mul_f32_e32 v89, v194, v194
	v_mul_f32_e32 v219, v195, v195
	v_mul_f32_e32 v130, v199, v199
	v_pk_add_f32 v[88:89], v[88:89], v[218:219]
	v_pk_fma_f32 v[218:219], v[198:199], v[198:199], v[130:131] op_sel_hi:[1,1,0]
	v_mul_f32_e32 v130, v197, v197
	v_pk_mul_f32 v[192:193], v[12:13], v[250:251]
	v_pk_fma_f32 v[244:245], v[196:197], v[196:197], v[130:131] op_sel_hi:[1,1,0]
	v_mul_f32_e32 v219, v192, v192
	v_mul_f32_e32 v245, v193, v193
	v_pk_add_f32 v[218:219], v[218:219], v[244:245]
	v_xor_b32_e32 v130, 16, v217
	v_pk_add_f32 v[88:89], v[88:89], v[218:219]
	s_nop 0
	v_add_f32_e32 v88, v88, v89
	v_and_b32_e32 v89, 64, v217
	v_add_u32_e32 v89, 64, v89
	v_cmp_lt_i32_e32 vcc, v130, v89
	s_nop 1
	v_cndmask_b32_e32 v130, v217, v130, vcc
	v_lshlrev_b32_e32 v244, 2, v130
	ds_bpermute_b32 v130, v244, v88
	s_waitcnt lgkmcnt(0)
	v_add_f32_e32 v88, v88, v130
	v_xor_b32_e32 v130, 32, v217
	v_cmp_lt_i32_e32 vcc, v130, v89
	s_nop 1
	v_cndmask_b32_e32 v89, v217, v130, vcc
	v_lshlrev_b32_e32 v245, 2, v89
	ds_bpermute_b32 v89, v245, v88
	s_waitcnt lgkmcnt(0)
	v_add_f32_e32 v88, v88, v89
	v_add_f32_e32 v88, 0x2b8cbccc, v88
	v_mul_f32_e32 v89, 0x4b800000, v88
	v_cmp_gt_f32_e32 vcc, s10, v88
	s_nop 1
	v_cndmask_b32_e32 v88, v88, v89, vcc
	v_rsq_f32_e32 v88, v88
	s_nop 0
	v_mul_f32_e32 v89, 0x45800000, v88
	v_cndmask_b32_e32 v130, v88, v89, vcc
	v_pk_mul_f32 v[88:89], v[86:87], v[130:131] op_sel_hi:[1,0]
	v_pk_mul_f32 v[86:87], v[224:225], v[130:131] op_sel_hi:[1,0]
	global_store_dwordx4 v[186:187], v[74:77], off sc1
	global_store_dwordx4 v[186:187], v[86:89], off offset:256 sc1
	ds_read_b128 v[246:249], v255
	s_waitcnt lgkmcnt(0)
	v_add_f32_e32 v218, v94, v246
	v_add_f32_e32 v219, v95, v247
	v_add_f32_e32 v224, v96, v248
	v_add_f32_e32 v96, v97, v249
	ds_read_b128 v[246:249], v255 offset:128
	v_mul_f32_e32 v97, 0xbfb8aa3b, v218
	v_exp_f32_e32 v97, v97
	v_mad_u64_u32 v[94:95], s[10:11], v204, s66, v[184:185]
	v_mad_i32_i24 v95, v205, s66, v95
	v_add_f32_e32 v97, 1.0, v97
	s_nop 1
	v_mul_f32_e32 v224, 0xbfb8aa3b, v224
	v_exp_f32_e32 v224, v224
	v_mul_f32_e32 v96, 0xbfb8aa3b, v96
	s_nop 3
	v_add_f32_e32 v224, 1.0, v224
	v_exp_f32_e32 v96, v96
	s_waitcnt lgkmcnt(0)
	v_add_f32_e32 v90, v90, v246
	s_nop 3
	v_mul_f32_e32 v205, 0xbfb8aa3b, v219
	v_exp_f32_e32 v205, v205
	v_add_f32_e32 v91, v91, v247
	v_mul_f32_e32 v90, 0xbfb8aa3b, v90
	v_mul_f32_e32 v91, 0xbfb8aa3b, v91
	v_add_f32_e32 v205, 1.0, v205
	s_nop 1
	v_exp_f32_e32 v90, v90
	v_exp_f32_e32 v91, v91
	v_add_f32_e32 v92, v92, v248
	s_nop 6
	v_pk_add_f32 v[90:91], v[90:91], 1.0 op_sel_hi:[1,0]
	s_nop 2
	v_add_f32_e32 v93, v93, v249
	v_add_f32_e32 v96, 1.0, v96
	v_rcp_f32_e32 v204, v97
	s_nop 0
	v_mul_f32_e32 v97, s45, v204
	s_nop 7
	v_mul_f32_e32 v97, 0x3fb8aa3b, v97
	v_rcp_f32_e32 v218, v205
	s_nop 0
	v_mul_f32_e32 v204, s45, v218
	v_mul_f32_e32 v204, 0x3fb8aa3b, v204
	s_nop 7
	s_nop 0
	s_nop 7
	s_nop 0
	s_nop 7
	v_exp_f32_e32 v246, v97
	v_rcp_f32_e32 v248, v224
	s_nop 0
	v_mul_f32_e32 v97, s45, v248
	v_rcp_f32_e32 v249, v96
	s_nop 0
	v_mul_f32_e32 v96, s45, v249
	v_mul_f32_e32 v97, 0x3fb8aa3b, v97
	v_mul_f32_e32 v96, 0x3fb8aa3b, v96
	v_exp_f32_e32 v248, v97
	v_exp_f32_e32 v249, v96
	v_rcp_f32_e32 v97, v91
	s_nop 0
	v_rcp_f32_e32 v96, v90
	s_nop 0
	v_mul_f32_e32 v90, 0xbfb8aa3b, v92
	v_mul_f32_e32 v91, 0xbfb8aa3b, v93
	v_exp_f32_e32 v90, v90
	v_exp_f32_e32 v91, v91
	v_exp_f32_e32 v247, v204
	v_pk_add_f32 v[90:91], v[90:91], 1.0 op_sel_hi:[1,0]
	s_nop 0
	s_nop 1
	global_store_dwordx4 v[94:95], v[246:249], off sc1
	s_nop 7
	s_nop 0
	s_nop 7
	v_rcp_f32_e32 v205, v91
	s_nop 0
	v_rcp_f32_e32 v204, v90
	s_nop 0
	v_xor_b32_e32 v91, 0x80000000, v97
	v_xor_b32_e32 v90, 0x80000000, v96
	v_xor_b32_e32 v93, 0x80000000, v205
	v_xor_b32_e32 v92, 0x80000000, v204
	v_pk_mul_f32 v[92:93], v[88:89], v[92:93]
	v_pk_mul_f32 v[90:91], v[86:87], v[90:91]
	global_store_dwordx4 v[94:95], v[90:93], off offset:256 sc1
	s_nop 1
	v_pk_add_f32 v[90:91], v[96:97], -1.0 op_sel_hi:[1,0]
	v_pk_add_f32 v[92:93], v[204:205], -1.0 op_sel_hi:[1,0]
	v_pk_fma_f32 v[90:91], v[78:79], v[90:91], 1.0 op_sel_hi:[1,1,0]
	v_pk_fma_f32 v[92:93], v[80:81], v[92:93], 1.0 op_sel_hi:[1,1,0]
	v_pk_mul_f32 v[90:91], v[46:47], v[90:91]
	v_pk_mul_f32 v[92:93], v[48:49], v[92:93]
	global_store_dwordx4 v[94:95], v[90:93], off offset:512 sc1
	ds_read_b128 v[246:249], v255 offset:64
	s_waitcnt lgkmcnt(0)
	v_add_f32_e32 v96, v82, v246
	v_add_f32_e32 v97, v83, v247
	v_add_f32_e32 v204, v84, v248
	v_add_f32_e32 v205, v85, v249
	ds_read_b128 v[82:85], v255 offset:192
	s_waitcnt lgkmcnt(0)
	v_add_f32_e32 v50, v50, v82
	v_mul_f32_e32 v82, 0xbfb8aa3b, v96
	v_exp_f32_e32 v82, v82
	v_add_f32_e32 v52, v52, v84
	v_add_f32_e32 v51, v51, v83
	v_add_f32_e32 v53, v53, v85
	v_add_f32_e32 v84, 1.0, v82
	s_nop 1
	v_mul_f32_e32 v50, 0xbfb8aa3b, v50
	v_mul_f32_e32 v51, 0xbfb8aa3b, v51
	v_exp_f32_e32 v50, v50
	s_nop 7
	v_mul_f32_e32 v82, 0xbfb8aa3b, v97
	v_exp_f32_e32 v82, v82
	v_exp_f32_e32 v51, v51
	v_mul_f32_e32 v52, 0xbfb8aa3b, v52
	v_mul_f32_e32 v53, 0xbfb8aa3b, v53
	v_add_f32_e32 v96, 1.0, v82
	s_nop 1
	v_pk_add_f32 v[50:51], v[50:51], 1.0 op_sel_hi:[1,0]
	v_exp_f32_e32 v52, v52
	v_exp_f32_e32 v53, v53
	s_nop 7
	v_pk_add_f32 v[52:53], v[52:53], 1.0 op_sel_hi:[1,0]
	s_nop 7
	v_rcp_f32_e32 v51, v51
	s_nop 0
	v_mul_f32_e32 v82, 0xbfb8aa3b, v204
	v_exp_f32_e32 v82, v82
	s_nop 6
	v_add_f32_e32 v204, 1.0, v82
	s_nop 1
	v_rcp_f32_e32 v50, v50
	s_nop 0
	s_nop 0
	s_nop 0
	s_nop 7
	v_mul_f32_e32 v82, 0xbfb8aa3b, v205
	v_exp_f32_e32 v82, v82
	s_nop 0
	v_add_f32_e32 v205, 1.0, v82
	s_nop 1
	s_nop 0
	s_nop 7
	s_nop 0
	s_nop 7
	v_rcp_f32_e32 v53, v53
	s_nop 0
	s_mov_b32 s10, 0x1800000
	s_nop 7
	v_rcp_f32_e32 v52, v52
	s_nop 0
	v_pk_add_f32 v[82:83], v[50:51], -1.0 op_sel_hi:[1,0]
	v_xor_b32_e32 v51, 0x80000000, v51
	v_pk_fma_f32 v[78:79], v[78:79], v[82:83], 1.0 op_sel_hi:[1,1,0]
	v_pk_add_f32 v[82:83], v[52:53], -1.0 op_sel_hi:[1,0]
	v_pk_mul_f32 v[46:47], v[46:47], v[78:79]
	v_pk_fma_f32 v[80:81], v[80:81], v[82:83], 1.0 op_sel_hi:[1,1,0]
	v_rcp_f32_e32 v85, v84
	s_nop 0
	v_mul_f32_e32 v78, s45, v85
	v_pk_mul_f32 v[48:49], v[48:49], v[80:81]
	v_rcp_f32_e32 v97, v96
	s_nop 0
	v_mul_f32_e32 v79, s45, v97
	v_rcp_f32_e32 v218, v204
	s_nop 0
	v_mul_f32_e32 v80, s45, v218
	v_rcp_f32_e32 v219, v205
	s_nop 0
	v_mul_f32_e32 v81, s45, v219
	v_mul_f32_e32 v78, 0x3fb8aa3b, v78
	v_mul_f32_e32 v79, 0x3fb8aa3b, v79
	v_mul_f32_e32 v80, 0x3fb8aa3b, v80
	v_mul_f32_e32 v81, 0x3fb8aa3b, v81
	v_exp_f32_e32 v78, v78
	v_exp_f32_e32 v79, v79
	v_exp_f32_e32 v80, v80
	v_exp_f32_e32 v81, v81
	v_add_co_u32_e32 v82, vcc, s10, v94
	v_xor_b32_e32 v50, 0x80000000, v50
	v_xor_b32_e32 v53, 0x80000000, v53
	v_xor_b32_e32 v52, 0x80000000, v52
	v_addc_co_u32_e32 v83, vcc, 0, v95, vcc
	v_pk_mul_f32 v[52:53], v[88:89], v[52:53]
	v_pk_mul_f32 v[50:51], v[86:87], v[50:51]
	global_store_dwordx4 v[82:83], v[78:81], off sc1
	global_store_dwordx4 v[82:83], v[50:53], off offset:256 sc1
	v_mul_f32_e32 v88, v74, v46
	v_mul_f32_e32 v89, v75, v47
	global_store_dwordx4 v[82:83], v[46:49], off offset:512 sc1
	v_mul_f32_e32 v84, v74, v90
	v_mul_f32_e32 v85, v75, v91
	v_lshl_add_u64 v[46:47], v[168:169], 2, v[190:191]
	v_mul_f32_e32 v86, v76, v92
	v_mul_f32_e32 v87, v77, v93
	v_mul_f32_e32 v90, v76, v48
	v_mul_f32_e32 v91, v77, v49
	global_load_dwordx4 v[74:77], v[46:47], off
	s_nop 0
	global_load_dwordx4 v[46:49], v[188:189], off offset:2112
	global_load_dwordx4 v[78:81], v[174:175], off offset:64
	global_load_dwordx4 v[50:53], v[176:177], off offset:64
	s_waitcnt vmcnt(0)
	global_store_dwordx4 v[186:187], v[74:77], off offset:576 sc1
	s_nop 1
	v_pk_mul_f32 v[76:77], v[200:201], v[130:131] op_sel_hi:[1,0]
	v_pk_mul_f32 v[74:75], v[202:203], v[130:131] op_sel_hi:[1,0]
	global_store_dwordx4 v[186:187], v[46:49], off offset:64 sc1
	global_store_dwordx4 v[186:187], v[74:77], off offset:320 sc1
	ds_read_b128 v[200:203], v255 offset:16
	s_waitcnt lgkmcnt(0)
	v_add_f32_e32 v92, v70, v200
	v_add_f32_e32 v93, v71, v201
	v_add_f32_e32 v96, v72, v202
	v_add_f32_e32 v97, v73, v203
	ds_read_b128 v[70:73], v255 offset:144
	s_waitcnt lgkmcnt(0)
	v_add_f32_e32 v72, v68, v72
	v_mul_f32_e32 v68, 0xbfb8aa3b, v92
	v_exp_f32_e32 v68, v68
	v_add_f32_e32 v73, v69, v73
	v_add_f32_e32 v66, v66, v70
	v_add_f32_e32 v67, v67, v71
	v_add_f32_e32 v68, 1.0, v68
	s_nop 1
	v_mul_f32_e32 v66, 0xbfb8aa3b, v66
	v_mul_f32_e32 v67, 0xbfb8aa3b, v67
	v_exp_f32_e32 v66, v66
	s_nop 7
	v_mul_f32_e32 v70, 0xbfb8aa3b, v93
	v_exp_f32_e32 v70, v70
	v_exp_f32_e32 v67, v67
	v_add_f32_e32 v92, 1.0, v70
	s_nop 1
	s_nop 0
	s_nop 7
	v_pk_add_f32 v[70:71], v[66:67], 1.0 op_sel_hi:[1,0]
	s_nop 0
	s_nop 1
	s_nop 0
	s_nop 7
	v_rcp_f32_e32 v71, v71
	s_nop 0
	s_nop 7
	v_mul_f32_e32 v66, 0xbfb8aa3b, v96
	v_exp_f32_e32 v66, v66
	v_rcp_f32_e32 v70, v70
	s_nop 0
	v_add_f32_e32 v96, 1.0, v66
	s_nop 1
	s_nop 0
	s_nop 7
	v_mul_f32_e32 v66, 0xbfb8aa3b, v97
	v_exp_f32_e32 v66, v66
	s_nop 0
	v_add_f32_e32 v97, 1.0, v66
	s_nop 1
	s_nop 0
	s_nop 7
	v_rcp_f32_e32 v69, v68
	s_nop 0
	v_mul_f32_e32 v66, s45, v69
	v_rcp_f32_e32 v93, v92
	s_nop 0
	v_mul_f32_e32 v67, s45, v93
	v_rcp_f32_e32 v202, v96
	s_nop 0
	v_mul_f32_e32 v68, s45, v202
	v_rcp_f32_e32 v203, v97
	s_nop 0
	v_mul_f32_e32 v69, s45, v203
	v_mul_f32_e32 v66, 0x3fb8aa3b, v66
	v_mul_f32_e32 v67, 0x3fb8aa3b, v67
	v_mul_f32_e32 v68, 0x3fb8aa3b, v68
	v_mul_f32_e32 v69, 0x3fb8aa3b, v69
	v_exp_f32_e32 v66, v66
	v_exp_f32_e32 v67, v67
	v_exp_f32_e32 v68, v68
	v_exp_f32_e32 v69, v69
	global_store_dwordx4 v[94:95], v[66:69], off offset:64 sc1
	s_nop 1
	v_mul_f32_e32 v66, 0xbfb8aa3b, v72
	v_mul_f32_e32 v67, 0xbfb8aa3b, v73
	v_exp_f32_e32 v66, v66
	v_exp_f32_e32 v67, v67
	s_nop 0
	v_pk_add_f32 v[66:67], v[66:67], 1.0 op_sel_hi:[1,0]
	s_nop 0
	s_nop 1
	s_nop 0
	s_nop 7
	s_nop 0
	s_nop 7
	v_rcp_f32_e32 v73, v67
	s_nop 0
	v_rcp_f32_e32 v72, v66
	s_nop 0
	v_xor_b32_e32 v67, 0x80000000, v71
	v_xor_b32_e32 v66, 0x80000000, v70
	v_xor_b32_e32 v69, 0x80000000, v73
	v_xor_b32_e32 v68, 0x80000000, v72
	v_pk_mul_f32 v[68:69], v[76:77], v[68:69]
	v_pk_mul_f32 v[66:67], v[74:75], v[66:67]
	global_store_dwordx4 v[94:95], v[66:69], off offset:320 sc1
	s_nop 1
	v_pk_add_f32 v[66:67], v[70:71], -1.0 op_sel_hi:[1,0]
	v_pk_add_f32 v[68:69], v[72:73], -1.0 op_sel_hi:[1,0]
	v_pk_fma_f32 v[66:67], v[78:79], v[66:67], 1.0 op_sel_hi:[1,1,0]
	v_pk_fma_f32 v[68:69], v[80:81], v[68:69], 1.0 op_sel_hi:[1,1,0]
	v_pk_mul_f32 v[66:67], v[54:55], v[66:67]
	v_pk_mul_f32 v[68:69], v[56:57], v[68:69]
	global_store_dwordx4 v[94:95], v[66:69], off offset:576 sc1
	ds_read_b128 v[70:73], v255 offset:80
	s_waitcnt lgkmcnt(0)
	v_add_f32_e32 v70, v62, v70
	v_add_f32_e32 v71, v63, v71
	v_add_f32_e32 v72, v64, v72
	v_add_f32_e32 v73, v65, v73
	ds_read_b128 v[62:65], v255 offset:208
	s_waitcnt lgkmcnt(0)
	v_add_f32_e32 v58, v58, v62
	v_mul_f32_e32 v62, 0xbfb8aa3b, v70
	v_exp_f32_e32 v62, v62
	v_add_f32_e32 v59, v59, v63
	v_add_f32_e32 v60, v60, v64
	v_add_f32_e32 v61, v61, v65
	v_add_f32_e32 v70, 1.0, v62
	s_nop 1
	v_mul_f32_e32 v58, 0xbfb8aa3b, v58
	v_mul_f32_e32 v59, 0xbfb8aa3b, v59
	v_exp_f32_e32 v58, v58
	s_nop 7
	v_mul_f32_e32 v62, 0xbfb8aa3b, v71
	v_exp_f32_e32 v62, v62
	v_exp_f32_e32 v59, v59
	v_mul_f32_e32 v60, 0xbfb8aa3b, v60
	v_mul_f32_e32 v61, 0xbfb8aa3b, v61
	v_add_f32_e32 v71, 1.0, v62
	s_nop 1
	v_pk_add_f32 v[58:59], v[58:59], 1.0 op_sel_hi:[1,0]
	v_exp_f32_e32 v60, v60
	v_exp_f32_e32 v61, v61
	s_nop 7
	v_pk_add_f32 v[60:61], v[60:61], 1.0 op_sel_hi:[1,0]
	s_nop 7
	v_rcp_f32_e32 v59, v59
	s_nop 0
	v_mul_f32_e32 v62, 0xbfb8aa3b, v72
	v_exp_f32_e32 v62, v62
	s_nop 6
	v_add_f32_e32 v72, 1.0, v62
	s_nop 1
	v_rcp_f32_e32 v58, v58
	s_nop 0
	s_nop 0
	s_nop 0
	s_nop 7
	v_mul_f32_e32 v62, 0xbfb8aa3b, v73
	v_exp_f32_e32 v62, v62
	s_nop 0
	v_add_f32_e32 v73, 1.0, v62
	s_nop 1
	s_nop 0
	s_nop 7
	s_nop 0
	s_nop 7
	v_rcp_f32_e32 v61, v61
	s_nop 0
	s_nop 7
	v_rcp_f32_e32 v60, v60
	s_nop 0
	v_pk_add_f32 v[62:63], v[58:59], -1.0 op_sel_hi:[1,0]
	v_pk_add_f32 v[64:65], v[60:61], -1.0 op_sel_hi:[1,0]
	v_pk_fma_f32 v[62:63], v[78:79], v[62:63], 1.0 op_sel_hi:[1,1,0]
	v_pk_fma_f32 v[64:65], v[80:81], v[64:65], 1.0 op_sel_hi:[1,1,0]
	v_pk_mul_f32 v[54:55], v[54:55], v[62:63]
	v_pk_mul_f32 v[56:57], v[56:57], v[64:65]
	v_rcp_f32_e32 v92, v70
	s_nop 0
	v_mul_f32_e32 v62, s45, v92
	v_rcp_f32_e32 v93, v71
	s_nop 0
	v_mul_f32_e32 v63, s45, v93
	v_rcp_f32_e32 v96, v72
	s_nop 0
	v_mul_f32_e32 v64, s45, v96
	v_rcp_f32_e32 v97, v73
	s_nop 0
	v_mul_f32_e32 v65, s45, v97
	v_mul_f32_e32 v62, 0x3fb8aa3b, v62
	v_mul_f32_e32 v63, 0x3fb8aa3b, v63
	v_mul_f32_e32 v64, 0x3fb8aa3b, v64
	v_mul_f32_e32 v65, 0x3fb8aa3b, v65
	v_exp_f32_e32 v62, v62
	v_exp_f32_e32 v63, v63
	v_exp_f32_e32 v64, v64
	v_exp_f32_e32 v65, v65
	v_xor_b32_e32 v59, 0x80000000, v59
	v_xor_b32_e32 v58, 0x80000000, v58
	v_xor_b32_e32 v61, 0x80000000, v61
	v_xor_b32_e32 v60, 0x80000000, v60
	v_pk_mul_f32 v[58:59], v[74:75], v[58:59]
	v_pk_mul_f32 v[60:61], v[76:77], v[60:61]
	global_store_dwordx4 v[82:83], v[62:65], off offset:64 sc1
	global_store_dwordx4 v[82:83], v[58:61], off offset:320 sc1
	global_store_dwordx4 v[82:83], v[54:57], off offset:576 sc1
	s_nop 0
	v_lshl_add_u64 v[58:59], v[170:171], 2, v[190:191]
	global_load_dwordx4 v[70:73], v[58:59], off
	s_nop 0
	global_load_dwordx4 v[58:61], v[188:189], off offset:2176
	global_load_dwordx4 v[74:77], v[174:175], off offset:128
	global_load_dwordx4 v[62:65], v[176:177], off offset:128
	s_waitcnt vmcnt(0)
	global_store_dwordx4 v[186:187], v[70:73], off offset:640 sc1
	s_nop 1
	v_pk_mul_f32 v[72:73], v[196:197], v[130:131] op_sel_hi:[1,0]
	v_pk_mul_f32 v[70:71], v[198:199], v[130:131] op_sel_hi:[1,0]
	global_store_dwordx4 v[186:187], v[58:61], off offset:128 sc1
	global_store_dwordx4 v[186:187], v[70:73], off offset:384 sc1
	ds_read_b128 v[78:81], v255 offset:32
	s_waitcnt lgkmcnt(0)
	v_add_f32_e32 v78, v42, v78
	v_add_f32_e32 v79, v43, v79
	v_add_f32_e32 v80, v44, v80
	v_add_f32_e32 v81, v45, v81
	ds_read_b128 v[42:45], v255 offset:160
	s_waitcnt lgkmcnt(0)
	v_add_f32_e32 v44, v40, v44
	v_mul_f32_e32 v40, 0xbfb8aa3b, v78
	v_exp_f32_e32 v40, v40
	v_add_f32_e32 v45, v41, v45
	v_add_f32_e32 v38, v38, v42
	v_add_f32_e32 v39, v39, v43
	v_add_f32_e32 v40, 1.0, v40
	s_nop 1
	v_mul_f32_e32 v38, 0xbfb8aa3b, v38
	v_mul_f32_e32 v39, 0xbfb8aa3b, v39
	v_exp_f32_e32 v38, v38
	s_nop 7
	v_mul_f32_e32 v42, 0xbfb8aa3b, v79
	v_exp_f32_e32 v42, v42
	v_exp_f32_e32 v39, v39
	v_add_f32_e32 v78, 1.0, v42
	s_nop 1
	s_nop 0
	s_nop 7
	v_pk_add_f32 v[42:43], v[38:39], 1.0 op_sel_hi:[1,0]
	s_nop 0
	s_nop 1
	s_nop 0
	s_nop 7
	v_rcp_f32_e32 v43, v43
	s_nop 0
	s_nop 7
	v_mul_f32_e32 v38, 0xbfb8aa3b, v80
	v_exp_f32_e32 v38, v38
	v_rcp_f32_e32 v42, v42
	s_nop 0
	v_add_f32_e32 v80, 1.0, v38
	s_nop 1
	s_nop 0
	s_nop 7
	v_mul_f32_e32 v38, 0xbfb8aa3b, v81
	v_exp_f32_e32 v38, v38
	s_nop 0
	v_add_f32_e32 v81, 1.0, v38
	s_nop 1
	s_nop 0
	s_nop 7
	v_rcp_f32_e32 v41, v40
	s_nop 0
	v_mul_f32_e32 v38, s45, v41
	v_rcp_f32_e32 v79, v78
	s_nop 0
	v_mul_f32_e32 v39, s45, v79
	v_rcp_f32_e32 v96, v80
	s_nop 0
	v_mul_f32_e32 v40, s45, v96
	v_rcp_f32_e32 v97, v81
	s_nop 0
	v_mul_f32_e32 v41, s45, v97
	v_mul_f32_e32 v38, 0x3fb8aa3b, v38
	v_mul_f32_e32 v39, 0x3fb8aa3b, v39
	v_mul_f32_e32 v40, 0x3fb8aa3b, v40
	v_mul_f32_e32 v41, 0x3fb8aa3b, v41
	v_exp_f32_e32 v38, v38
	v_exp_f32_e32 v39, v39
	v_exp_f32_e32 v40, v40
	v_exp_f32_e32 v41, v41
	global_store_dwordx4 v[94:95], v[38:41], off offset:128 sc1
	s_nop 1
	v_mul_f32_e32 v38, 0xbfb8aa3b, v44
	v_mul_f32_e32 v39, 0xbfb8aa3b, v45
	v_exp_f32_e32 v38, v38
	v_exp_f32_e32 v39, v39
	s_nop 0
	v_pk_add_f32 v[38:39], v[38:39], 1.0 op_sel_hi:[1,0]
	s_nop 0
	s_nop 1
	s_nop 0
	s_nop 7
	s_nop 0
	s_nop 7
	v_rcp_f32_e32 v45, v39
	s_nop 0
	v_rcp_f32_e32 v44, v38
	s_nop 0
	v_xor_b32_e32 v39, 0x80000000, v43
	v_xor_b32_e32 v38, 0x80000000, v42
	v_xor_b32_e32 v41, 0x80000000, v45
	v_xor_b32_e32 v40, 0x80000000, v44
	v_pk_mul_f32 v[40:41], v[72:73], v[40:41]
	v_pk_mul_f32 v[38:39], v[70:71], v[38:39]
	global_store_dwordx4 v[94:95], v[38:41], off offset:384 sc1
	s_nop 1
	v_pk_add_f32 v[38:39], v[42:43], -1.0 op_sel_hi:[1,0]
	v_pk_add_f32 v[40:41], v[44:45], -1.0 op_sel_hi:[1,0]
	v_pk_fma_f32 v[38:39], v[74:75], v[38:39], 1.0 op_sel_hi:[1,1,0]
	v_pk_fma_f32 v[40:41], v[76:77], v[40:41], 1.0 op_sel_hi:[1,1,0]
	v_pk_mul_f32 v[38:39], v[26:27], v[38:39]
	v_pk_mul_f32 v[40:41], v[28:29], v[40:41]
	global_store_dwordx4 v[94:95], v[38:41], off offset:640 sc1
	ds_read_b128 v[42:45], v255 offset:96
	s_waitcnt lgkmcnt(0)
	v_add_f32_e32 v42, v34, v42
	v_add_f32_e32 v43, v35, v43
	v_add_f32_e32 v44, v36, v44
	v_add_f32_e32 v45, v37, v45
	ds_read_b128 v[34:37], v255 offset:224
	s_waitcnt lgkmcnt(0)
	v_add_f32_e32 v30, v30, v34
	v_mul_f32_e32 v34, 0xbfb8aa3b, v42
	v_exp_f32_e32 v34, v34
	v_add_f32_e32 v31, v31, v35
	v_add_f32_e32 v32, v32, v36
	v_add_f32_e32 v33, v33, v37
	v_add_f32_e32 v42, 1.0, v34
	s_nop 1
	v_mul_f32_e32 v30, 0xbfb8aa3b, v30
	v_mul_f32_e32 v31, 0xbfb8aa3b, v31
	v_exp_f32_e32 v30, v30
	s_nop 7
	v_mul_f32_e32 v34, 0xbfb8aa3b, v43
	v_exp_f32_e32 v34, v34
	v_exp_f32_e32 v31, v31
	v_mul_f32_e32 v32, 0xbfb8aa3b, v32
	v_mul_f32_e32 v33, 0xbfb8aa3b, v33
	v_add_f32_e32 v43, 1.0, v34
	s_nop 1
	v_pk_add_f32 v[30:31], v[30:31], 1.0 op_sel_hi:[1,0]
	v_exp_f32_e32 v32, v32
	v_exp_f32_e32 v33, v33
	s_nop 7
	v_pk_add_f32 v[32:33], v[32:33], 1.0 op_sel_hi:[1,0]
	s_nop 7
	v_rcp_f32_e32 v31, v31
	s_nop 0
	v_mul_f32_e32 v34, 0xbfb8aa3b, v44
	v_exp_f32_e32 v34, v34
	s_nop 6
	v_add_f32_e32 v44, 1.0, v34
	s_nop 1
	v_rcp_f32_e32 v30, v30
	s_nop 0
	s_nop 0
	s_nop 0
	s_nop 7
	v_mul_f32_e32 v34, 0xbfb8aa3b, v45
	v_exp_f32_e32 v34, v34
	s_nop 0
	v_add_f32_e32 v45, 1.0, v34
	s_nop 1
	s_nop 0
	s_nop 7
	s_nop 0
	s_nop 7
	v_rcp_f32_e32 v33, v33
	s_nop 0
	s_nop 7
	v_rcp_f32_e32 v32, v32
	s_nop 0
	v_pk_add_f32 v[34:35], v[30:31], -1.0 op_sel_hi:[1,0]
	v_pk_add_f32 v[36:37], v[32:33], -1.0 op_sel_hi:[1,0]
	v_pk_fma_f32 v[34:35], v[74:75], v[34:35], 1.0 op_sel_hi:[1,1,0]
	v_pk_fma_f32 v[36:37], v[76:77], v[36:37], 1.0 op_sel_hi:[1,1,0]
	v_pk_mul_f32 v[74:75], v[26:27], v[34:35]
	v_pk_mul_f32 v[76:77], v[28:29], v[36:37]
	v_xor_b32_e32 v27, 0x80000000, v31
	v_xor_b32_e32 v26, 0x80000000, v30
	v_xor_b32_e32 v29, 0x80000000, v33
	v_xor_b32_e32 v28, 0x80000000, v32
	v_rcp_f32_e32 v78, v42
	s_nop 0
	v_mul_f32_e32 v30, s45, v78
	v_rcp_f32_e32 v79, v43
	s_nop 0
	v_mul_f32_e32 v31, s45, v79
	v_rcp_f32_e32 v80, v44
	s_nop 0
	v_mul_f32_e32 v32, s45, v80
	v_rcp_f32_e32 v81, v45
	s_nop 0
	v_mul_f32_e32 v33, s45, v81
	v_mul_f32_e32 v30, 0x3fb8aa3b, v30
	v_mul_f32_e32 v31, 0x3fb8aa3b, v31
	v_mul_f32_e32 v32, 0x3fb8aa3b, v32
	v_mul_f32_e32 v33, 0x3fb8aa3b, v33
	v_exp_f32_e32 v30, v30
	v_exp_f32_e32 v31, v31
	v_exp_f32_e32 v32, v32
	v_exp_f32_e32 v33, v33
	v_pk_mul_f32 v[28:29], v[72:73], v[28:29]
	v_pk_mul_f32 v[26:27], v[70:71], v[26:27]
	global_store_dwordx4 v[82:83], v[30:33], off offset:128 sc1
	global_store_dwordx4 v[82:83], v[26:29], off offset:384 sc1
	global_store_dwordx4 v[82:83], v[74:77], off offset:640 sc1
	v_lshl_add_u64 v[30:31], v[172:173], 2, v[190:191]
	global_load_dwordx4 v[70:73], v[30:31], off
	s_nop 0
	global_load_dwordx4 v[30:33], v[188:189], off offset:2240
	global_load_dwordx4 v[42:45], v[174:175], off offset:192
	global_load_dwordx4 v[34:37], v[176:177], off offset:192
	v_pk_mul_f32 v[28:29], v[192:193], v[130:131] op_sel_hi:[1,0]
	v_pk_mul_f32 v[26:27], v[194:195], v[130:131] op_sel_hi:[1,0]
	s_waitcnt vmcnt(0)
	global_store_dwordx4 v[186:187], v[70:73], off offset:704 sc1
	global_store_dwordx4 v[186:187], v[30:33], off offset:192 sc1
	global_store_dwordx4 v[186:187], v[26:29], off offset:448 sc1
	ds_read_b128 v[70:73], v255 offset:48
	s_waitcnt lgkmcnt(0)
	v_add_f32_e32 v70, v18, v70
	v_add_f32_e32 v71, v19, v71
	v_add_f32_e32 v72, v20, v72
	v_add_f32_e32 v73, v21, v73
	ds_read_b128 v[18:21], v255 offset:176
	s_waitcnt lgkmcnt(0)
	v_add_f32_e32 v15, v15, v19
	v_add_f32_e32 v19, v16, v20
	v_mul_f32_e32 v16, 0xbfb8aa3b, v70
	v_exp_f32_e32 v16, v16
	v_add_f32_e32 v78, v17, v21
	v_add_f32_e32 v14, v14, v18
	v_fma_f32 v18, v22, v84, 0
	v_add_f32_e32 v16, 1.0, v16
	s_nop 1
	v_fmac_f32_e32 v18, v23, v85
	v_fmac_f32_e32 v18, v24, v86
	v_fmac_f32_e32 v18, v25, v87
	s_nop 2
	v_fmac_f32_e32 v18, v22, v88
	s_nop 0
	v_fmac_f32_e32 v18, v23, v89
	s_nop 3
	v_mul_f32_e32 v20, 0xbfb8aa3b, v71
	v_exp_f32_e32 v20, v20
	v_mul_f32_e32 v14, 0xbfb8aa3b, v14
	v_mul_f32_e32 v15, 0xbfb8aa3b, v15
	v_fmac_f32_e32 v18, v24, v90
	v_add_f32_e32 v22, 1.0, v20
	s_nop 1
	v_exp_f32_e32 v14, v14
	v_exp_f32_e32 v15, v15
	v_fmac_f32_e32 v18, v25, v91
	s_nop 7
	v_pk_add_f32 v[20:21], v[14:15], 1.0 op_sel_hi:[1,0]
	s_nop 0
	s_nop 1
	s_nop 0
	s_nop 7
	v_rcp_f32_e32 v21, v21
	s_nop 0
	s_nop 7
	v_mul_f32_e32 v14, 0xbfb8aa3b, v72
	v_exp_f32_e32 v14, v14
	v_rcp_f32_e32 v20, v20
	s_nop 0
	v_add_f32_e32 v70, 1.0, v14
	s_nop 1
	s_nop 0
	s_nop 7
	v_mul_f32_e32 v14, 0xbfb8aa3b, v73
	v_exp_f32_e32 v14, v14
	s_nop 0
	v_add_f32_e32 v72, 1.0, v14
	s_nop 1
	s_nop 0
	s_nop 7
	v_rcp_f32_e32 v17, v16
	s_nop 0
	v_mul_f32_e32 v14, s45, v17
	v_rcp_f32_e32 v23, v22
	s_nop 0
	v_mul_f32_e32 v15, s45, v23
	v_rcp_f32_e32 v71, v70
	s_nop 0
	v_mul_f32_e32 v16, s45, v71
	v_rcp_f32_e32 v73, v72
	s_nop 0
	v_mul_f32_e32 v17, s45, v73
	v_mul_f32_e32 v14, 0x3fb8aa3b, v14
	v_mul_f32_e32 v15, 0x3fb8aa3b, v15
	v_mul_f32_e32 v16, 0x3fb8aa3b, v16
	v_mul_f32_e32 v17, 0x3fb8aa3b, v17
	v_exp_f32_e32 v14, v14
	v_exp_f32_e32 v15, v15
	v_exp_f32_e32 v16, v16
	v_exp_f32_e32 v17, v17
	global_store_dwordx4 v[94:95], v[14:17], off offset:192 sc1
	s_nop 1
	v_mul_f32_e32 v14, 0xbfb8aa3b, v19
	v_mul_f32_e32 v15, 0xbfb8aa3b, v78
	v_exp_f32_e32 v14, v14
	v_exp_f32_e32 v15, v15
	s_nop 0
	v_pk_add_f32 v[14:15], v[14:15], 1.0 op_sel_hi:[1,0]
	s_nop 0
	s_nop 1
	s_nop 0
	s_nop 7
	s_nop 0
	s_nop 7
	v_rcp_f32_e32 v23, v15
	s_nop 0
	v_rcp_f32_e32 v22, v14
	s_nop 0
	v_xor_b32_e32 v15, 0x80000000, v21
	v_xor_b32_e32 v14, 0x80000000, v20
	v_xor_b32_e32 v17, 0x80000000, v23
	v_xor_b32_e32 v16, 0x80000000, v22
	v_pk_mul_f32 v[16:17], v[28:29], v[16:17]
	v_pk_mul_f32 v[14:15], v[26:27], v[14:15]
	global_store_dwordx4 v[94:95], v[14:17], off offset:448 sc1
	v_mul_f32_e32 v19, v46, v66
	v_fmac_f32_e32 v18, v50, v19
	v_pk_add_f32 v[14:15], v[20:21], -1.0 op_sel_hi:[1,0]
	v_mul_f32_e32 v19, v47, v67
	v_pk_fma_f32 v[14:15], v[42:43], v[14:15], 1.0 op_sel_hi:[1,1,0]
	v_fmac_f32_e32 v18, v51, v19
	v_pk_mul_f32 v[20:21], v[10:11], v[14:15]
	v_pk_add_f32 v[14:15], v[22:23], -1.0 op_sel_hi:[1,0]
	v_mul_f32_e32 v19, v48, v68
	v_pk_fma_f32 v[14:15], v[44:45], v[14:15], 1.0 op_sel_hi:[1,1,0]
	v_fmac_f32_e32 v18, v52, v19
	v_pk_mul_f32 v[22:23], v[12:13], v[14:15]
	global_store_dwordx4 v[94:95], v[20:23], off offset:704 sc1
	ds_read_b128 v[14:17], v255 offset:112
	v_mul_f32_e32 v19, v49, v69
	ds_read_b128 v[66:69], v255 offset:240
	v_fmac_f32_e32 v18, v53, v19
	v_mul_f32_e32 v19, v46, v54
	v_fmac_f32_e32 v18, v50, v19
	v_mul_f32_e32 v19, v47, v55
	v_fmac_f32_e32 v18, v51, v19
	v_mul_f32_e32 v19, v48, v56
	v_fmac_f32_e32 v18, v52, v19
	v_mul_f32_e32 v19, v49, v57
	v_fmac_f32_e32 v18, v53, v19
	v_mul_f32_e32 v19, v58, v38
	v_fmac_f32_e32 v18, v62, v19
	v_mul_f32_e32 v19, v59, v39
	v_fmac_f32_e32 v18, v63, v19
	v_mul_f32_e32 v19, v60, v40
	v_fmac_f32_e32 v18, v64, v19
	v_mul_f32_e32 v19, v61, v41
	v_fmac_f32_e32 v18, v65, v19
	v_mul_f32_e32 v19, v58, v74
	v_fmac_f32_e32 v18, v62, v19
	v_mul_f32_e32 v19, v59, v75
	v_fmac_f32_e32 v18, v63, v19
	v_mul_f32_e32 v19, v60, v76
	v_fmac_f32_e32 v18, v64, v19
	v_mul_f32_e32 v19, v61, v77
	v_fmac_f32_e32 v18, v65, v19
	v_mul_f32_e32 v19, v30, v20
	v_fmac_f32_e32 v18, v34, v19
	s_waitcnt lgkmcnt(0)
	v_add_f32_e32 v2, v2, v14
	v_mul_f32_e32 v2, 0xbfb8aa3b, v2
	v_exp_f32_e32 v2, v2
	v_mul_f32_e32 v14, v31, v21
	v_fmac_f32_e32 v18, v35, v14
	v_mul_f32_e32 v14, v32, v22
	v_add_f32_e32 v2, 1.0, v2
	s_nop 1
	v_add_f32_e32 v3, v3, v15
	v_fmac_f32_e32 v18, v36, v14
	v_mul_f32_e32 v14, v33, v23
	v_mul_f32_e32 v3, 0xbfb8aa3b, v3
	v_fmac_f32_e32 v18, v37, v14
	s_nop 0
	v_exp_f32_e32 v3, v3
	s_nop 4
	v_add_f32_e32 v15, 1.0, v3
	s_nop 0
	v_div_scale_f32 v19, s[10:11], v15, v15, s45
	s_nop 0
	v_rcp_f32_e32 v20, v19
	v_rcp_f32_e32 v14, v2
	s_nop 0
	v_mul_f32_e32 v2, s45, v14
	v_mul_f32_e32 v2, 0x3fb8aa3b, v2
	v_exp_f32_e32 v14, v2
	v_fma_f32 v3, -v19, v20, 1.0
	v_add_f32_e32 v2, v6, v66
	v_fmac_f32_e32 v20, v3, v20
	v_div_scale_f32 v6, vcc, s45, v15, s45
	v_mul_f32_e32 v21, v6, v20
	v_fma_f32 v3, -v19, v21, v6
	v_fmac_f32_e32 v21, v3, v20
	v_add_f32_e32 v3, v7, v67
	v_mul_f32_e32 v2, 0xbfb8aa3b, v2
	v_mul_f32_e32 v3, 0xbfb8aa3b, v3
	v_exp_f32_e32 v2, v2
	v_exp_f32_e32 v3, v3
	v_fma_f32 v6, -v19, v21, v6
	v_div_fmas_f32 v6, v6, v20, v21
	v_div_fixup_f32 v6, v6, v15, s45
	v_pk_add_f32 v[2:3], v[2:3], 1.0 op_sel_hi:[1,0]
	v_mul_f32_e32 v6, 0x3fb8aa3b, v6
	s_nop 1
	v_exp_f32_e32 v15, v6
	v_add_f32_e32 v4, v4, v16
	v_mul_f32_e32 v4, 0xbfb8aa3b, v4
	s_nop 7
	v_rcp_f32_e32 v3, v3
	s_nop 0
	v_exp_f32_e32 v4, v4
	s_nop 7
	v_rcp_f32_e32 v2, v2
	s_nop 0
	v_pk_add_f32 v[6:7], v[2:3], -1.0 op_sel_hi:[1,0]
	v_add_f32_e32 v4, 1.0, v4
	v_pk_fma_f32 v[6:7], v[42:43], v[6:7], 1.0 op_sel_hi:[1,1,0]
	v_add_f32_e32 v5, v5, v17
	v_pk_mul_f32 v[6:7], v[10:11], v[6:7]
	s_nop 1
	v_mul_f32_e32 v10, v30, v6
	v_fmac_f32_e32 v18, v34, v10
	v_mul_f32_e32 v10, v31, v7
	v_fmac_f32_e32 v18, v35, v10
	s_nop 3
	v_mul_f32_e32 v5, 0xbfb8aa3b, v5
	s_nop 0
	v_exp_f32_e32 v5, v5
	s_nop 2
	v_rcp_f32_e32 v10, v4
	s_nop 0
	v_mul_f32_e32 v4, s45, v10
	v_add_f32_e32 v10, 1.0, v5
	v_div_scale_f32 v11, s[10:11], v10, v10, s45
	v_rcp_f32_e32 v17, v11
	v_mul_f32_e32 v4, 0x3fb8aa3b, v4
	v_exp_f32_e32 v16, v4
	v_add_f32_e32 v4, v8, v68
	v_fma_f32 v5, -v11, v17, 1.0
	v_fmac_f32_e32 v17, v5, v17
	v_div_scale_f32 v8, vcc, s45, v10, s45
	v_mul_f32_e32 v19, v8, v17
	v_fma_f32 v5, -v11, v19, v8
	v_fmac_f32_e32 v19, v5, v17
	v_add_f32_e32 v5, v9, v69
	v_mul_f32_e32 v4, 0xbfb8aa3b, v4
	v_mul_f32_e32 v5, 0xbfb8aa3b, v5
	v_exp_f32_e32 v4, v4
	v_exp_f32_e32 v5, v5
	v_fma_f32 v8, -v11, v19, v8
	v_div_fmas_f32 v8, v8, v17, v19
	v_div_fixup_f32 v8, v8, v10, s45
	v_pk_add_f32 v[4:5], v[4:5], 1.0 op_sel_hi:[1,0]
	v_mul_f32_e32 v8, 0x3fb8aa3b, v8
	s_nop 1
	v_exp_f32_e32 v17, v8
	s_nop 7
	v_rcp_f32_e32 v5, v5
	s_nop 0
	s_nop 7
	v_rcp_f32_e32 v4, v4
	s_nop 0
	v_pk_add_f32 v[8:9], v[4:5], -1.0 op_sel_hi:[1,0]
	v_xor_b32_e32 v11, 0x80000000, v3
	v_pk_fma_f32 v[8:9], v[44:45], v[8:9], 1.0 op_sel_hi:[1,1,0]
	s_nop 0
	v_pk_mul_f32 v[8:9], v[12:13], v[8:9]
	s_nop 0
	v_mul_f32_e32 v10, v32, v8
	v_fmac_f32_e32 v18, v36, v10
	v_mul_f32_e32 v3, v33, v9
	v_fmac_f32_e32 v18, v37, v3
	ds_bpermute_b32 v19, v244, v18
	v_xor_b32_e32 v10, 0x80000000, v2
	v_xor_b32_e32 v3, 0x80000000, v5
	v_xor_b32_e32 v2, 0x80000000, v4
	v_pk_mul_f32 v[12:13], v[28:29], v[2:3]
	s_waitcnt lgkmcnt(0)
	v_add_f32_e32 v2, v18, v19
	ds_bpermute_b32 v3, v245, v2
	v_pk_mul_f32 v[10:11], v[26:27], v[10:11]
	global_store_dwordx4 v[82:83], v[14:17], off offset:192 sc1
	global_store_dwordx4 v[82:83], v[10:13], off offset:448 sc1
	global_store_dwordx4 v[82:83], v[6:9], off offset:704 sc1
	s_and_saveexec_b64 s[10:11], s[6:7]
	s_cbranch_execz .LBB0_473
	s_waitcnt lgkmcnt(0)
	v_add_f32_e32 v4, v2, v3
	v_lshl_add_u32 v2, v243, 2, v98
	v_ashrrev_i32_e32 v3, 31, v2
	v_lshl_add_u64 v[2:3], v[2:3], 2, s[52:53]
	global_store_dword v[2:3], v4, off sc1
	s_branch .LBB0_473

.LBB0_605:
	s_or_b64 exec, exec, s[0:1]
	s_waitcnt lgkmcnt(0)
	s_barrier
	ds_read_b32 v1, v131 offset:228
	s_movk_i32 s0, 0x2ff
	s_waitcnt lgkmcnt(0)
	s_barrier
	v_cmp_lt_i32_e32 vcc, s0, v1
	v_readfirstlane_b32 s20, v1
	s_mov_b64 s[0:1], -1
	s_cbranch_vccnz .LBB0_600
	s_cmpk_gt_i32 s20, 0xff
	s_cbranch_scc0 .LBB0_702
	s_cmpk_gt_u32 s20, 0x1ff
	s_cbranch_scc0 .LBB0_612
	v_mov_b32_e32 v1, v0
	ds_read_b64 v[2:3], v131 offset:88
	s_and_b32 s0, s20, 3
	v_readlane_b32 s4, v254, 63
	s_or_b32 s10, s0, s4
	s_lshl_b32 s96, s10, 14
	s_lshl_b32 s1, s20, 5
	s_waitcnt lgkmcnt(0)
	v_readfirstlane_b32 s7, v2
	s_lshl_b64 s[4:5], s[96:97], 2
	v_lshlrev_b32_e32 v2, 2, v1
	v_readfirstlane_b32 s6, v3
	s_add_u32 s4, s7, s4
	v_and_b32_e32 v2, 0x7c, v2
	v_ashrrev_i32_e32 v3, 5, v1
	s_addc_u32 s5, s6, s5
	v_lshlrev_b32_e32 v130, 2, v2
	s_waitcnt vmcnt(9)
	v_lshlrev_b32_e32 v6, 7, v3
	v_lshl_add_u64 v[4:5], s[4:5], 0, v[130:131]
	v_ashrrev_i32_e32 v7, 31, v6
	v_lshl_add_u64 v[6:7], v[6:7], 2, v[4:5]
	s_barrier
	v_lshl_add_u32 v2, v2, 1, v212
	v_lshl_add_u32 v30, v3, 9, v130
	v_mul_u32_u24_e32 v31, 0x110, v3
	v_add_u32_e32 v31, v31, v2
	global_load_dwordx4 v[6:9], v30, s[4:5]
	s_add_u32 s4, s4, 0x2000
	s_addc_u32 s5, s5, 0
	global_load_dwordx4 v[10:13], v30, s[4:5]
	s_add_u32 s4, s4, 0x2000
	s_addc_u32 s5, s5, 0
	global_load_dwordx4 v[14:17], v30, s[4:5]
	s_add_u32 s4, s4, 0x2000
	s_addc_u32 s5, s5, 0
	global_load_dwordx4 v[18:21], v30, s[4:5]
	s_add_u32 s4, s4, 0x2000
	s_addc_u32 s5, s5, 0
	global_load_dwordx4 v[22:25], v30, s[4:5]
	s_add_u32 s4, s4, 0x2000
	s_addc_u32 s5, s5, 0
	global_load_dwordx4 v[26:29], v30, s[4:5]
	s_add_u32 s4, s4, 0x2000
	s_addc_u32 s5, s5, 0
	global_load_dwordx4 v[32:35], v30, s[4:5]
	s_add_u32 s4, s4, 0x2000
	s_addc_u32 s5, s5, 0
	global_load_dwordx4 v[36:39], v30, s[4:5]
	s_movk_i32 s6, 0x110
	s_waitcnt vmcnt(7)
	v_cvt_pk_bf16_f32 v6, v6, v7
	v_cvt_pk_bf16_f32 v7, v8, v9
	ds_write_b64 v31, v[6:7]
	s_waitcnt vmcnt(6)
	v_cvt_pk_bf16_f32 v10, v10, v11
	v_cvt_pk_bf16_f32 v11, v12, v13
	ds_write_b64 v31, v[10:11] offset:4352
	s_waitcnt vmcnt(5)
	v_cvt_pk_bf16_f32 v14, v14, v15
	v_cvt_pk_bf16_f32 v15, v16, v17
	ds_write_b64 v31, v[14:15] offset:8704
	s_waitcnt vmcnt(4)
	v_cvt_pk_bf16_f32 v18, v18, v19
	v_cvt_pk_bf16_f32 v19, v20, v21
	ds_write_b64 v31, v[18:19] offset:13056
	s_waitcnt vmcnt(3)
	v_cvt_pk_bf16_f32 v22, v22, v23
	v_cvt_pk_bf16_f32 v23, v24, v25
	ds_write_b64 v31, v[22:23] offset:17408
	s_waitcnt vmcnt(2)
	v_cvt_pk_bf16_f32 v26, v26, v27
	v_cvt_pk_bf16_f32 v27, v28, v29
	ds_write_b64 v31, v[26:27] offset:21760
	s_waitcnt vmcnt(1)
	v_cvt_pk_bf16_f32 v32, v32, v33
	v_cvt_pk_bf16_f32 v33, v34, v35
	ds_write_b64 v31, v[32:33] offset:26112
	s_waitcnt vmcnt(0)
	v_cvt_pk_bf16_f32 v36, v36, v37
	v_cvt_pk_bf16_f32 v37, v38, v39
	ds_write_b64 v31, v[36:37] offset:30464
	s_lshl_b32 s11, s0, 6
	s_and_b32 s12, s1, 0x1f80
	s_movk_i32 s13, 0x5ff
	s_mul_i32 s4, s12, 0x2200
	s_add_u32 s4, s28, s4
	s_addc_u32 s5, s29, 0
	s_lshl_b32 s6, s11, 2
	s_add_u32 s4, s4, s6
	s_addc_u32 s5, s5, 0
	v_lshrrev_b32_e32 v8, 4, v0
	v_lshlrev_b32_e32 v9, 2, v0
	v_and_b32_e32 v9, 60, v9
	v_mul_u32_u24_e32 v22, 0x2200, v8
	v_lshl_add_u32 v22, v9, 2, v22
	global_load_dwordx4 v[4:7], v22, s[4:5] offset:1024
	s_add_u32 s4, s4, 0x44000
	s_addc_u32 s5, s5, 0
	global_load_dwordx4 v[10:13], v22, s[4:5] offset:1024
	s_add_u32 s4, s4, 0x44000
	s_addc_u32 s5, s5, 0
	global_load_dwordx4 v[14:17], v22, s[4:5] offset:1024
	s_add_u32 s4, s4, 0x44000
	s_addc_u32 s5, s5, 0
	global_load_dwordx4 v[18:21], v22, s[4:5] offset:1024
	v_mul_u32_u24_e32 v23, 0x110, v9
	v_lshl_add_u32 v23, v8, 1, v23
	v_add_u32_e32 v23, s73, v23
	s_waitcnt vmcnt(3)
	v_cvt_pk_bf16_f32 v24, v4, v131
	ds_write_b16 v23, v24 offset:34816
	v_cvt_pk_bf16_f32 v24, v5, v131
	ds_write_b16 v23, v24 offset:35088
	v_cvt_pk_bf16_f32 v24, v6, v131
	ds_write_b16 v23, v24 offset:35360
	v_cvt_pk_bf16_f32 v24, v7, v131
	ds_write_b16 v23, v24 offset:35632
	s_waitcnt vmcnt(2)
	v_cvt_pk_bf16_f32 v24, v10, v131
	ds_write_b16 v23, v24 offset:34880
	v_cvt_pk_bf16_f32 v24, v11, v131
	ds_write_b16 v23, v24 offset:35152
	v_cvt_pk_bf16_f32 v24, v12, v131
	ds_write_b16 v23, v24 offset:35424
	v_cvt_pk_bf16_f32 v24, v13, v131
	ds_write_b16 v23, v24 offset:35696
	s_waitcnt vmcnt(1)
	v_cvt_pk_bf16_f32 v24, v14, v131
	ds_write_b16 v23, v24 offset:34944
	v_cvt_pk_bf16_f32 v24, v15, v131
	ds_write_b16 v23, v24 offset:35216
	v_cvt_pk_bf16_f32 v24, v16, v131
	ds_write_b16 v23, v24 offset:35488
	v_cvt_pk_bf16_f32 v24, v17, v131
	ds_write_b16 v23, v24 offset:35760
	s_waitcnt vmcnt(0)
	v_cvt_pk_bf16_f32 v24, v18, v131
	ds_write_b16 v23, v24 offset:35008
	v_cvt_pk_bf16_f32 v24, v19, v131
	ds_write_b16 v23, v24 offset:35280
	v_cvt_pk_bf16_f32 v24, v20, v131
	ds_write_b16 v23, v24 offset:35552
	v_cvt_pk_bf16_f32 v24, v21, v131
	ds_write_b16 v23, v24 offset:35824
	v_bfe_u32 v28, v1, 4, 2
	v_ashrrev_i32_e32 v2, 2, v1
	v_and_b32_e32 v7, 15, v1
	v_bfi_b32 v1, -16, v2, v1
	v_lshl_add_u32 v6, v28, 4, v212
	s_movk_i32 s4, 0x110
	v_mad_u64_u32 v[26:27], s[0:1], v1, s4, v[6:7]
	v_mad_u32_u24 v27, v7, s4, v6
	s_waitcnt lgkmcnt(0)
	s_barrier
	ds_read_b128 v[2:5], v26
	ds_read_b128 v[6:9], v27 offset:34816
	ds_read_b128 v[10:13], v27 offset:39168
	ds_read_b128 v[14:17], v27 offset:43520
	ds_read_b128 v[18:21], v27 offset:47872
	s_waitcnt lgkmcnt(3)
	v_mfma_f32_16x16x32_bf16 v[6:9], v[6:9], v[2:5], 0
	v_lshl_or_b32 v30, v28, 2, s11
	v_lshlrev_b32_e32 v130, 2, v30
	v_readlane_b32 s79, v254, 50
	s_waitcnt lgkmcnt(2)
	v_mfma_f32_16x16x32_bf16 v[10:13], v[10:13], v[2:5], 0
	s_waitcnt lgkmcnt(1)
	v_mfma_f32_16x16x32_bf16 v[14:17], v[14:17], v[2:5], 0
	s_waitcnt lgkmcnt(0)
	v_mfma_f32_16x16x32_bf16 v[2:5], v[18:21], v[2:5], 0
	ds_read_b128 v[18:21], v26 offset:64
	ds_read_b128 v[22:25], v27 offset:34880
	s_waitcnt lgkmcnt(0)
	v_mfma_f32_16x16x32_bf16 v[6:9], v[22:25], v[18:21], v[6:9]
	ds_read_b128 v[22:25], v27 offset:39232
	s_waitcnt lgkmcnt(0)
	v_mfma_f32_16x16x32_bf16 v[10:13], v[22:25], v[18:21], v[10:13]
	ds_read_b128 v[22:25], v27 offset:43584
	s_waitcnt lgkmcnt(0)
	v_mfma_f32_16x16x32_bf16 v[14:17], v[22:25], v[18:21], v[14:17]
	ds_read_b128 v[22:25], v27 offset:47936
	s_waitcnt lgkmcnt(0)
	v_mfma_f32_16x16x32_bf16 v[2:5], v[22:25], v[18:21], v[2:5]
	ds_read_b128 v[18:21], v26 offset:128
	ds_read_b128 v[22:25], v27 offset:34944
	s_waitcnt lgkmcnt(0)
	v_mfma_f32_16x16x32_bf16 v[6:9], v[22:25], v[18:21], v[6:9]
	ds_read_b128 v[22:25], v27 offset:39296
	s_waitcnt lgkmcnt(0)
	v_mfma_f32_16x16x32_bf16 v[10:13], v[22:25], v[18:21], v[10:13]
	ds_read_b128 v[22:25], v27 offset:43648
	s_waitcnt lgkmcnt(0)
	v_mfma_f32_16x16x32_bf16 v[14:17], v[22:25], v[18:21], v[14:17]
	ds_read_b128 v[22:25], v27 offset:48000
	s_waitcnt lgkmcnt(0)
	v_mfma_f32_16x16x32_bf16 v[2:5], v[22:25], v[18:21], v[2:5]
	ds_read_b128 v[18:21], v26 offset:192
	ds_read_b128 v[22:25], v27 offset:35008
	s_waitcnt lgkmcnt(0)
	v_mfma_f32_16x16x32_bf16 v[22:25], v[22:25], v[18:21], v[6:9]
	s_nop 2
	ds_read_b128 v[6:9], v27 offset:39360
	s_waitcnt lgkmcnt(0)
	v_mfma_f32_16x16x32_bf16 v[10:13], v[6:9], v[18:21], v[10:13]
	ds_read_b128 v[6:9], v27 offset:43712
	s_waitcnt lgkmcnt(0)
	v_mfma_f32_16x16x32_bf16 v[6:9], v[6:9], v[18:21], v[14:17]
	s_nop 2
	ds_read_b128 v[14:17], v27 offset:48064
	s_waitcnt lgkmcnt(0)
	v_mfma_f32_16x16x32_bf16 v[2:5], v[14:17], v[18:21], v[2:5]
	ds_read_b64 v[16:17], v131 offset:96
	v_lshl_add_u32 v18, s10, 7, v1
	v_ashrrev_i32_e32 v19, 31, v18
	v_add_u32_e32 v14, s12, v1
	v_ashrrev_i32_e32 v15, 31, v14
	s_waitcnt lgkmcnt(0)
	v_readfirstlane_b32 s0, v17
	v_readfirstlane_b32 s1, v16
	s_nop 0
	v_mov_b32_e32 v17, s0
	v_mov_b32_e32 v16, s1
	v_lshl_add_u64 v[16:17], v[18:19], 2, v[16:17]
	global_load_dword v1, v[16:17], off
	v_mov_b64_e32 v[16:17], s[28:29]
	v_mad_i64_i32 v[16:17], s[0:1], v14, s36, v[16:17]
	v_lshlrev_b64 v[14:15], 11, v[14:15]
	v_readlane_b32 s0, v253, 55
	v_lshl_add_u64 v[26:27], s[30:31], 0, v[14:15]
	v_readlane_b32 s1, v253, 56
	v_lshl_add_u64 v[16:17], v[16:17], 0, v[130:131]
	v_lshlrev_b32_e32 v130, 1, v30
	v_lshl_add_u64 v[28:29], s[0:1], 0, v[14:15]
	v_lshl_add_u64 v[14:15], v[26:27], 0, v[130:131]
	global_load_dwordx4 v[32:35], v[16:17], off
	global_load_dwordx4 v[36:39], v[16:17], off offset:64
	global_load_dwordx4 v[40:43], v[16:17], off offset:128
	global_load_dwordx4 v[44:47], v[16:17], off offset:192
	global_load_dwordx2 v[48:49], v[14:15], off
	global_load_dwordx2 v[50:51], v[14:15], off offset:32
	global_load_dwordx2 v[52:53], v[14:15], off offset:64
	global_load_dwordx2 v[54:55], v[14:15], off offset:96
	s_mov_b64 s[0:1], 0
	v_lshl_add_u64 v[18:19], v[28:29], 0, v[130:131]
	s_waitcnt vmcnt(0) lgkmcnt(0)
	v_add_f32_e32 v22, v22, v1
	v_mul_f32_e32 v22, v22, v32
	v_lshlrev_b32_e32 v56, 16, v48
	v_mul_f32_e32 v22, v22, v56
	v_add_f32_e32 v23, v23, v1
	v_mul_f32_e32 v23, v23, v33
	v_and_b32_e32 v56, 0xffff0000, v48
	v_mul_f32_e32 v23, v23, v56
	v_add_f32_e32 v24, v24, v1
	v_mul_f32_e32 v24, v24, v34
	v_lshlrev_b32_e32 v56, 16, v49
	v_mul_f32_e32 v24, v24, v56
	v_add_f32_e32 v25, v25, v1
	v_mul_f32_e32 v25, v25, v35
	v_and_b32_e32 v56, 0xffff0000, v49
	v_mul_f32_e32 v25, v25, v56
	v_cvt_pk_bf16_f32 v22, v22, v23
	v_cvt_pk_bf16_f32 v23, v24, v25
	global_store_dwordx2 v[18:19], v[22:23], off
	v_add_f32_e32 v10, v10, v1
	v_mul_f32_e32 v10, v10, v36
	v_lshlrev_b32_e32 v56, 16, v50
	v_mul_f32_e32 v10, v10, v56
	v_add_f32_e32 v11, v11, v1
	v_mul_f32_e32 v11, v11, v37
	v_and_b32_e32 v56, 0xffff0000, v50
	v_mul_f32_e32 v11, v11, v56
	v_add_f32_e32 v12, v12, v1
	v_mul_f32_e32 v12, v12, v38
	v_lshlrev_b32_e32 v56, 16, v51
	v_mul_f32_e32 v12, v12, v56
	v_add_f32_e32 v13, v13, v1
	v_mul_f32_e32 v13, v13, v39
	v_and_b32_e32 v56, 0xffff0000, v51
	v_mul_f32_e32 v13, v13, v56
	v_cvt_pk_bf16_f32 v10, v10, v11
	v_cvt_pk_bf16_f32 v11, v12, v13
	global_store_dwordx2 v[18:19], v[10:11], off offset:32
	v_add_f32_e32 v6, v6, v1
	v_mul_f32_e32 v6, v6, v40
	v_lshlrev_b32_e32 v56, 16, v52
	v_mul_f32_e32 v6, v6, v56
	v_add_f32_e32 v7, v7, v1
	v_mul_f32_e32 v7, v7, v41
	v_and_b32_e32 v56, 0xffff0000, v52
	v_mul_f32_e32 v7, v7, v56
	v_add_f32_e32 v8, v8, v1
	v_mul_f32_e32 v8, v8, v42
	v_lshlrev_b32_e32 v56, 16, v53
	v_mul_f32_e32 v8, v8, v56
	v_add_f32_e32 v9, v9, v1
	v_mul_f32_e32 v9, v9, v43
	v_and_b32_e32 v56, 0xffff0000, v53
	v_mul_f32_e32 v9, v9, v56
	v_cvt_pk_bf16_f32 v6, v6, v7
	v_cvt_pk_bf16_f32 v7, v8, v9
	global_store_dwordx2 v[18:19], v[6:7], off offset:64
	v_add_f32_e32 v2, v2, v1
	v_mul_f32_e32 v2, v2, v44
	v_lshlrev_b32_e32 v56, 16, v54
	v_mul_f32_e32 v2, v2, v56
	v_add_f32_e32 v3, v3, v1
	v_mul_f32_e32 v3, v3, v45
	v_and_b32_e32 v56, 0xffff0000, v54
	v_mul_f32_e32 v3, v3, v56
	v_add_f32_e32 v4, v4, v1
	v_mul_f32_e32 v4, v4, v46
	v_lshlrev_b32_e32 v56, 16, v55
	v_mul_f32_e32 v4, v4, v56
	v_add_f32_e32 v5, v5, v1
	v_mul_f32_e32 v5, v5, v47
	v_and_b32_e32 v56, 0xffff0000, v55
	v_mul_f32_e32 v5, v5, v56
	v_cvt_pk_bf16_f32 v2, v2, v3
	v_cvt_pk_bf16_f32 v3, v4, v5
	global_store_dwordx2 v[18:19], v[2:3], off offset:96
	s_nop 0
	s_nop 0
	s_nop 0
	s_nop 0
	s_nop 0
	s_nop 0
	s_nop 0
	s_nop 0
	s_nop 1
	s_nop 0
	s_nop 0
	s_nop 0
	s_nop 0
	s_nop 0
	s_nop 0
	s_nop 1
	s_nop 0
	s_nop 0
	s_nop 0
	s_nop 0
	s_nop 0
	s_nop 0
	s_nop 1
	s_nop 0
	s_nop 0
	s_nop 0
	s_nop 1
	s_nop 0

.LBB0_713:
	s_mov_b32 s0, 0x3e000000
	s_waitcnt vmcnt(1)
	v_pk_mul_f32 v[6:7], v[6:7], s[0:1] op_sel_hi:[1,0]
	s_waitcnt vmcnt(0)
	v_pk_mul_f32 v[4:5], v[4:5], s[0:1] op_sel_hi:[1,0]
	v_pk_mul_f32 v[2:3], v[2:3], s[0:1] op_sel_hi:[1,0]
	v_pk_mul_f32 v[8:9], v[8:9], s[0:1] op_sel_hi:[1,0]
	v_cvt_pk_bf16_f32 v6, v6, v7
	v_bfe_u32 v43, v42, 4, 2
	v_cvt_pk_bf16_f32 v7, v8, v9
	v_cvt_pk_bf16_f32 v2, v2, v3
	v_cvt_pk_bf16_f32 v3, v4, v5
	v_mul_lo_u32 v4, v13, s62
	v_add3_u32 v1, v1, v4, v12
	ds_write2_b64 v1, v[6:7], v[2:3] offset1:4
	v_ashrrev_i32_e32 v1, 2, v42
	v_bfi_b32 v101, -16, v1, v42
	v_mul_lo_u32 v2, v101, s62
	v_lshlrev_b32_e32 v3, 4, v43
	v_add3_u32 v6, s73, v2, v3
	s_waitcnt lgkmcnt(0)
	s_barrier
	ds_read_b128 v[2:5], v6
	ds_read_b128 v[6:9], v6 offset:64
	ds_read_b64 v[10:11], v131 offset:176
	v_readlane_b32 s0, v254, 63
	s_or_b32 s96, s10, s0
	s_lshl_b64 s[0:1], s[96:97], 2
	s_mov_b64 s[20:21], -1
	s_waitcnt lgkmcnt(0)
	v_readfirstlane_b32 s5, v10
	v_readfirstlane_b32 s4, v11
	s_add_u32 s0, s5, s0
	s_addc_u32 s1, s4, s1
	v_mov_b64_e32 v[10:11], s[0:1]
	global_load_dword v117, v[10:11], off
	ds_read_b128 v[10:13], v131 offset:16
	s_lshl_b32 s0, s10, 5
	s_and_b32 s59, s0, 64
	s_mov_b64 s[4:5], -1
	s_andn2_b64 vcc, exec, s[14:15]
	s_waitcnt lgkmcnt(0)
	v_readfirstlane_b32 s56, v10
	v_cndmask_b32_e64 v10, 0, 1, s[14:15]
	v_readfirstlane_b32 s55, v11
	v_readfirstlane_b32 s57, v13
	v_readfirstlane_b32 s58, v12
	v_cmp_ne_u32_e64 s[0:1], 1, v10
	s_cbranch_vccnz .LBB0_715
	s_mul_i32 s14, s52, 0x2200
	s_mul_hi_i32 s13, s52, 0x2200
	s_add_u32 s14, s28, s14
	s_addc_u32 s13, s29, s13
	s_lshl_b32 s15, s59, 2
	s_add_u32 s20, s14, s15
	s_addc_u32 s13, s13, 0
	s_add_u32 s14, s20, 0x1a00
	s_addc_u32 s15, s13, 0
	s_add_u32 s22, s20, 0x1c00
	s_addc_u32 s23, s13, 0
	s_mov_b64 s[20:21], 0

.LBB0_743:
	s_andn2_b64 vcc, exec, s[24:25]
	s_cbranch_vccz .LBB0_745
	v_mad_u64_u32 v[26:27], s[14:15], s63, v96, 0
	v_mad_u64_u32 v[34:35], s[14:15], s63, v100, 0
	v_mov_b32_e32 v28, v27
	v_mov_b32_e32 v36, v35
	v_mad_u64_u32 v[10:11], s[14:15], s63, v90, 0
	v_mad_u64_u32 v[20:21], s[14:15], s63, v94, 0
	v_mad_u64_u32 v[28:29], s[14:15], s63, v93, v[28:29]
	v_mad_u64_u32 v[36:37], s[14:15], s63, v97, v[36:37]
	v_mov_b32_e32 v12, v11
	v_mov_b32_e32 v22, v21
	v_mov_b32_e32 v27, v28
	v_mad_u64_u32 v[28:29], s[14:15], s63, v98, 0
	v_mov_b32_e32 v35, v36
	v_mad_u64_u32 v[36:37], s[14:15], s63, v102, 0
	v_mad_u64_u32 v[12:13], s[14:15], s63, v1, v[12:13]
	v_mad_u64_u32 v[22:23], s[14:15], s63, v91, v[22:23]
	v_mov_b32_e32 v30, v29
	v_mov_b32_e32 v38, v37
	v_mov_b32_e32 v11, v12
	v_mov_b32_e32 v21, v22
	v_mad_u64_u32 v[30:31], s[14:15], s63, v95, v[30:31]
	v_mad_u64_u32 v[38:39], s[14:15], s63, v99, v[38:39]
	v_lshl_add_u64 v[10:11], v[10:11], 2, s[6:7]
	v_lshl_add_u64 v[20:21], v[20:21], 2, s[6:7]
	v_mov_b32_e32 v29, v30
	v_mov_b32_e32 v37, v38
	v_lshl_add_u64 v[10:11], v[10:11], 0, v[130:131]
	v_lshlrev_b32_e32 v18, 2, v92
	v_mov_b32_e32 v19, v131
	v_lshl_add_u64 v[20:21], v[20:21], 0, v[130:131]
	v_lshl_add_u64 v[26:27], v[26:27], 2, s[20:21]
	v_mov_b32_e32 v105, v131
	v_lshl_add_u64 v[28:29], v[28:29], 2, s[20:21]
	v_lshl_add_u64 v[34:35], v[34:35], 2, s[20:21]
	v_lshl_add_u64 v[36:37], v[36:37], 2, s[20:21]
	v_lshl_add_u64 v[14:15], v[10:11], 0, v[18:19]
	v_lshl_add_u64 v[22:23], v[20:21], 0, v[18:19]
	v_lshl_add_u64 v[26:27], v[26:27], 0, v[104:105]
	v_lshl_add_u64 v[30:31], v[28:29], 0, v[104:105]
	v_lshl_add_u64 v[34:35], v[34:35], 0, v[104:105]
	v_lshl_add_u64 v[38:39], v[36:37], 0, v[104:105]
	global_load_dwordx4 v[10:13], v[14:15], off
	s_nop 0
	global_load_dwordx4 v[14:17], v[14:15], off offset:64
	s_nop 0
	global_load_dwordx4 v[18:21], v[22:23], off
	s_nop 0
	global_load_dwordx4 v[22:25], v[22:23], off offset:64
	s_nop 0
	global_load_dwordx4 v[26:29], v[26:27], off
	s_nop 0
	global_load_dwordx4 v[30:33], v[30:31], off
	s_nop 0
	global_load_dwordx4 v[34:37], v[34:35], off
	s_nop 0
	global_load_dwordx4 v[38:41], v[38:39], off
	s_mov_b32 s10, s11
	s_mov_b64 s[14:15], s[6:7]
	s_mov_b64 s[22:23], s[20:21]
	s_mov_b32 s61, s63
	s_mov_b32 s13, s12
	s_mov_b64 s[84:85], s[70:71]
	s_mov_b64 s[78:79], s[76:77]

.LBB0_807:
	s_or_b64 exec, exec, s[0:1]
	v_mov_b32_e32 v1, v0
	s_waitcnt lgkmcnt(0)
	v_mov_b32_e32 v2, v0
	s_barrier
	s_waitcnt vmcnt(9)
	ds_read_b128 v[4:7], v131 offset:160
	v_ashrrev_i32_e32 v2, 6, v2
	v_readlane_b32 s4, v253, 4
	s_waitcnt lgkmcnt(0)
	v_readfirstlane_b32 s6, v6
	v_add_u32_e32 v6, s4, v2
	s_movk_i32 s4, 0x2000
	v_readfirstlane_b32 s1, v5
	v_readfirstlane_b32 s7, v4
	v_readfirstlane_b32 s0, v7
	v_cmp_gt_i32_e32 vcc, s4, v6
	s_and_saveexec_b64 s[4:5], vcc
	v_readlane_b32 s10, v254, 28
	v_readlane_b32 s11, v254, 29
	v_readlane_b32 s12, v254, 30
	v_readlane_b32 s11, v254, 52
	v_readlane_b32 s13, v254, 31
	s_mov_b32 s14, 0x3c800000
	s_cbranch_execz .LBB0_810
	s_add_u32 s8, s7, s94
	v_and_b32_e32 v3, 63, v1
	s_addc_u32 s9, s1, s95
	s_add_u32 s6, s6, s94
	v_lshlrev_b32_e32 v130, 2, v3
	s_addc_u32 s7, s0, s95
	v_lshl_add_u64 v[4:5], s[8:9], 0, v[130:131]
	v_lshl_add_u64 v[8:9], s[6:7], 0, v[130:131]
	global_load_dword v1, v[4:5], off
	s_waitcnt vmcnt(0)
	global_load_dword v24, v[4:5], off offset:256
	global_load_dword v25, v[4:5], off offset:512
	global_load_dword v26, v[4:5], off offset:768
	global_load_dword v27, v[8:9], off
	global_load_dword v28, v[8:9], off offset:256
	global_load_dword v29, v[8:9], off offset:512
	global_load_dword v30, v[8:9], off offset:768
	v_and_b32_e32 v5, 64, v217
	v_xor_b32_e32 v4, 16, v217
	v_add_u32_e32 v5, 64, v5
	v_cmp_lt_i32_e32 vcc, v4, v5
	v_readlane_b32 s0, v253, 57
	v_readlane_b32 s1, v253, 58
	v_cndmask_b32_e32 v4, v217, v4, vcc
	v_lshlrev_b32_e32 v31, 2, v4
	v_xor_b32_e32 v4, 32, v217
	v_cmp_lt_i32_e32 vcc, v4, v5
	v_ashrrev_i32_e32 v7, 31, v6
	v_lshl_add_u64 v[8:9], s[0:1], 0, v[130:131]
	v_cndmask_b32_e32 v4, v217, v4, vcc
	v_lshlrev_b64 v[10:11], 11, v[6:7]
	v_lshlrev_b64 v[12:13], 10, v[6:7]
	v_readlane_b32 s0, v254, 24
	v_lshlrev_b32_e32 v32, 2, v4
	v_lshl_or_b32 v10, v3, 1, v10
	v_or_b32_e32 v12, v12, v130
	v_lshl_add_u32 v14, v2, 2, s0
	s_mov_b64 s[6:7], 0
